# select: exact pre-filter (per-lane 2 smallest over even/odd chunks -> bound tau, pass 0 histograms only keys <= tau), pass-2 early-out; S5 WP block 16 loads in flight
# speedup vs baseline: 1.0150x; 1.0016x over previous
.LBB0_495:
	v_lshl_or_b32 v132, s20, 14, v149
	v_ashrrev_i32_e32 v5, 31, v132
	v_mov_b32_e32 v4, v132
	v_lshl_add_u64 v[98:99], v[4:5], 1, v[152:153]
	v_add_co_u32_e32 v100, vcc, s27, v98
	v_lshl_add_u64 v[96:97], v[132:133], 1, v[152:153]
	s_nop 0
	v_addc_co_u32_e32 v101, vcc, 0, v99, vcc
	v_add_co_u32_e32 v102, vcc, s41, v98
	s_lshl_b32 s21, s20, 3
	s_nop 0
	v_addc_co_u32_e32 v103, vcc, 0, v99, vcc
	v_add_co_u32_e32 v104, vcc, s42, v98
	s_or_b32 s22, s21, 7
	s_nop 0
	v_addc_co_u32_e32 v105, vcc, 0, v99, vcc
	s_or_b32 s23, s21, 1
	s_or_b32 s24, s21, 3
	s_or_b32 s25, s21, 5
	v_mov_b64_e32 v[168:169], v[162:163]
	v_mov_b32_e32 v132, v182
	s_mov_b32 s33, 0
	s_nop 0
	global_load_dwordx4 v[184:187], v[96:97], off
	global_load_dwordx4 v[188:191], v[96:97], off offset:32
	global_load_dwordx4 v[192:195], v[96:97], off offset:64
	global_load_dwordx4 v[196:199], v[96:97], off offset:96
	global_load_dwordx4 v[200:203], v[96:97], off offset:128
	global_load_dwordx4 v[204:207], v[96:97], off offset:160
	global_load_dwordx4 v[208:211], v[96:97], off offset:192
	global_load_dwordx4 v[212:215], v[96:97], off offset:224
	global_load_dwordx4 v[216:219], v[100:101], off
	global_load_dwordx4 v[220:223], v[100:101], off offset:32
	global_load_dwordx4 v[224:227], v[100:101], off offset:64
	global_load_dwordx4 v[228:231], v[100:101], off offset:96
	global_load_dwordx4 v[232:235], v[100:101], off offset:128
	global_load_dwordx4 v[236:239], v[100:101], off offset:160
	global_load_dwordx4 v[240:243], v[100:101], off offset:192
	global_load_dwordx4 v[244:247], v[100:101], off offset:224
	s_waitcnt vmcnt(15) lgkmcnt(7)
	v_mfma_f32_32x32x16_bf16 v[48:63], v[184:187], v[64:67], 0
	global_load_dwordx4 v[184:187], v[102:103], off
	s_waitcnt vmcnt(15) lgkmcnt(6)
	v_mfma_f32_32x32x16_bf16 v[48:63], v[188:191], v[68:71], v[48:63]
	global_load_dwordx4 v[188:191], v[102:103], off offset:32
	s_waitcnt vmcnt(15) lgkmcnt(5)
	v_mfma_f32_32x32x16_bf16 v[48:63], v[192:195], v[72:75], v[48:63]
	global_load_dwordx4 v[192:195], v[102:103], off offset:64
	s_waitcnt vmcnt(15) lgkmcnt(4)
	v_mfma_f32_32x32x16_bf16 v[48:63], v[196:199], v[76:79], v[48:63]
	global_load_dwordx4 v[196:199], v[102:103], off offset:96
	s_waitcnt vmcnt(15) lgkmcnt(3)
	v_mfma_f32_32x32x16_bf16 v[48:63], v[200:203], v[80:83], v[48:63]
	global_load_dwordx4 v[200:203], v[102:103], off offset:128
	s_waitcnt vmcnt(15) lgkmcnt(2)
	v_mfma_f32_32x32x16_bf16 v[48:63], v[204:207], v[84:87], v[48:63]
	global_load_dwordx4 v[204:207], v[102:103], off offset:160
	s_waitcnt vmcnt(15) lgkmcnt(1)
	v_mfma_f32_32x32x16_bf16 v[48:63], v[208:211], v[88:91], v[48:63]
	global_load_dwordx4 v[208:211], v[102:103], off offset:192
	s_waitcnt vmcnt(15) lgkmcnt(0)
	v_mfma_f32_32x32x16_bf16 v[48:63], v[212:215], v[92:95], v[48:63]
	global_load_dwordx4 v[212:215], v[102:103], off offset:224
	s_waitcnt vmcnt(15)
	v_mfma_f32_32x32x16_bf16 v[32:47], v[216:219], v[64:67], 0
	global_load_dwordx4 v[216:219], v[104:105], off
	s_waitcnt vmcnt(15)
	v_mfma_f32_32x32x16_bf16 v[32:47], v[220:223], v[68:71], v[32:47]
	global_load_dwordx4 v[220:223], v[104:105], off offset:32
	s_waitcnt vmcnt(15)
	v_mfma_f32_32x32x16_bf16 v[32:47], v[224:227], v[72:75], v[32:47]
	global_load_dwordx4 v[224:227], v[104:105], off offset:64
	s_waitcnt vmcnt(15)
	v_mfma_f32_32x32x16_bf16 v[32:47], v[228:231], v[76:79], v[32:47]
	global_load_dwordx4 v[228:231], v[104:105], off offset:96
	s_waitcnt vmcnt(15)
	v_mfma_f32_32x32x16_bf16 v[32:47], v[232:235], v[80:83], v[32:47]
	global_load_dwordx4 v[232:235], v[104:105], off offset:128
	s_waitcnt vmcnt(15)
	v_mfma_f32_32x32x16_bf16 v[32:47], v[236:239], v[84:87], v[32:47]
	global_load_dwordx4 v[236:239], v[104:105], off offset:160
	s_waitcnt vmcnt(15)
	v_mfma_f32_32x32x16_bf16 v[32:47], v[240:243], v[88:91], v[32:47]
	global_load_dwordx4 v[240:243], v[104:105], off offset:192
	s_waitcnt vmcnt(15)
	v_mfma_f32_32x32x16_bf16 v[32:47], v[244:247], v[92:95], v[32:47]
	global_load_dwordx4 v[244:247], v[104:105], off offset:224
	s_waitcnt vmcnt(15)
	v_mfma_f32_32x32x16_bf16 v[16:31], v[184:187], v[64:67], 0
	s_waitcnt vmcnt(14)
	v_mfma_f32_32x32x16_bf16 v[16:31], v[188:191], v[68:71], v[16:31]
	s_waitcnt vmcnt(13)
	v_mfma_f32_32x32x16_bf16 v[16:31], v[192:195], v[72:75], v[16:31]
	s_waitcnt vmcnt(12)
	v_mfma_f32_32x32x16_bf16 v[16:31], v[196:199], v[76:79], v[16:31]
	s_waitcnt vmcnt(11)
	v_mfma_f32_32x32x16_bf16 v[16:31], v[200:203], v[80:83], v[16:31]
	s_waitcnt vmcnt(10)
	v_mfma_f32_32x32x16_bf16 v[16:31], v[204:207], v[84:87], v[16:31]
	s_waitcnt vmcnt(9)
	v_mfma_f32_32x32x16_bf16 v[16:31], v[208:211], v[88:91], v[16:31]
	s_waitcnt vmcnt(8)
	v_mfma_f32_32x32x16_bf16 v[16:31], v[212:215], v[92:95], v[16:31]
	s_waitcnt vmcnt(7)
	v_mfma_f32_32x32x16_bf16 v[0:15], v[216:219], v[64:67], 0
	s_waitcnt vmcnt(6)
	v_mfma_f32_32x32x16_bf16 v[0:15], v[220:223], v[68:71], v[0:15]
	s_waitcnt vmcnt(5)
	v_mfma_f32_32x32x16_bf16 v[0:15], v[224:227], v[72:75], v[0:15]
	s_waitcnt vmcnt(4)
	v_mfma_f32_32x32x16_bf16 v[0:15], v[228:231], v[76:79], v[0:15]
	s_waitcnt vmcnt(3)
	v_mfma_f32_32x32x16_bf16 v[0:15], v[232:235], v[80:83], v[0:15]
	s_waitcnt vmcnt(2)
	v_mfma_f32_32x32x16_bf16 v[0:15], v[236:239], v[84:87], v[0:15]
	s_waitcnt vmcnt(1)
	v_mfma_f32_32x32x16_bf16 v[0:15], v[240:243], v[88:91], v[0:15]
	s_waitcnt vmcnt(0)
	v_mfma_f32_32x32x16_bf16 v[0:15], v[244:247], v[92:95], v[0:15]
	s_branch .LBB0_498

.Lsel_start:
	s_mov_b64 exec, -1
	v_mbcnt_lo_u32_b32 v131, -1, 0
	v_mbcnt_hi_u32_b32 v131, -1, v131
	v_lshlrev_b32_e32 v133, 2, v131
	v_mov_b32_e32 v135, 1
	v_readfirstlane_b32 s16, v146
	s_lshr_b32 s16, s16, 6
	s_lshl_b32 s93, s16, 13
	s_add_i32 s93, s93, 73728
	v_mov_b32_e32 v136, s93
	s_movk_i32 s95, 0x1ffc
	s_ashr_i32 s17, s63, 9
	s_and_b32 s93, s63, 0x1ff
	s_sub_i32 s94, 0x2ff, s93
	s_cmpk_lt_u32 s93, 0x100
	s_cselect_b32 s93, s93, s94
	s_lshl_b32 s18, s93, 4
	s_mov_b32 s19, 0

.Lsel_ld_done:
	s_waitcnt vmcnt(0)
	v_mov_b32_e32 v150, -1
	v_mov_b32_e32 v151, -1
	v_mov_b32_e32 v249, -1
	v_mov_b32_e32 v137, -1
	s_cmpk_ge_u32 s33, 1024
	s_cbranch_scc0 .Lsel_cv_slow0
	v_xor_b32_e32 v240, 0x7fffffff, v0
	v_ashrrev_i32_e32 v241, 31, v0
	v_bfi_b32 v0, v241, v0, v240
	v_max_u32_e32 v240, v150, v0
	v_min_u32_e32 v150, v150, v0
	v_min_u32_e32 v151, v151, v240
	v_xor_b32_e32 v242, 0x7fffffff, v1
	v_ashrrev_i32_e32 v243, 31, v1
	v_bfi_b32 v1, v243, v1, v242
	v_max_u32_e32 v242, v249, v1
	v_min_u32_e32 v249, v249, v1
	v_min_u32_e32 v137, v137, v242
	v_xor_b32_e32 v244, 0x7fffffff, v2
	v_ashrrev_i32_e32 v245, 31, v2
	v_bfi_b32 v2, v245, v2, v244
	v_max_u32_e32 v244, v150, v2
	v_min_u32_e32 v150, v150, v2
	v_min_u32_e32 v151, v151, v244
	v_xor_b32_e32 v246, 0x7fffffff, v3
	v_ashrrev_i32_e32 v247, 31, v3
	v_bfi_b32 v3, v247, v3, v246
	v_max_u32_e32 v246, v249, v3
	v_min_u32_e32 v249, v249, v3
	v_min_u32_e32 v137, v137, v246
	v_xor_b32_e32 v240, 0x7fffffff, v4
	v_ashrrev_i32_e32 v241, 31, v4
	v_bfi_b32 v4, v241, v4, v240
	v_max_u32_e32 v240, v150, v4
	v_min_u32_e32 v150, v150, v4
	v_min_u32_e32 v151, v151, v240
	v_xor_b32_e32 v242, 0x7fffffff, v5
	v_ashrrev_i32_e32 v243, 31, v5
	v_bfi_b32 v5, v243, v5, v242
	v_max_u32_e32 v242, v249, v5
	v_min_u32_e32 v249, v249, v5
	v_min_u32_e32 v137, v137, v242
	v_xor_b32_e32 v244, 0x7fffffff, v6
	v_ashrrev_i32_e32 v245, 31, v6
	v_bfi_b32 v6, v245, v6, v244
	v_max_u32_e32 v244, v150, v6
	v_min_u32_e32 v150, v150, v6
	v_min_u32_e32 v151, v151, v244
	v_xor_b32_e32 v246, 0x7fffffff, v7
	v_ashrrev_i32_e32 v247, 31, v7
	v_bfi_b32 v7, v247, v7, v246
	v_max_u32_e32 v246, v249, v7
	v_min_u32_e32 v249, v249, v7
	v_min_u32_e32 v137, v137, v246
	v_xor_b32_e32 v240, 0x7fffffff, v8
	v_ashrrev_i32_e32 v241, 31, v8
	v_bfi_b32 v8, v241, v8, v240
	v_max_u32_e32 v240, v150, v8
	v_min_u32_e32 v150, v150, v8
	v_min_u32_e32 v151, v151, v240
	v_xor_b32_e32 v242, 0x7fffffff, v9
	v_ashrrev_i32_e32 v243, 31, v9
	v_bfi_b32 v9, v243, v9, v242
	v_max_u32_e32 v242, v249, v9
	v_min_u32_e32 v249, v249, v9
	v_min_u32_e32 v137, v137, v242
	v_xor_b32_e32 v244, 0x7fffffff, v10
	v_ashrrev_i32_e32 v245, 31, v10
	v_bfi_b32 v10, v245, v10, v244
	v_max_u32_e32 v244, v150, v10
	v_min_u32_e32 v150, v150, v10
	v_min_u32_e32 v151, v151, v244
	v_xor_b32_e32 v246, 0x7fffffff, v11
	v_ashrrev_i32_e32 v247, 31, v11
	v_bfi_b32 v11, v247, v11, v246
	v_max_u32_e32 v246, v249, v11
	v_min_u32_e32 v249, v249, v11
	v_min_u32_e32 v137, v137, v246
	v_xor_b32_e32 v240, 0x7fffffff, v12
	v_ashrrev_i32_e32 v241, 31, v12
	v_bfi_b32 v12, v241, v12, v240
	v_max_u32_e32 v240, v150, v12
	v_min_u32_e32 v150, v150, v12
	v_min_u32_e32 v151, v151, v240
	v_xor_b32_e32 v242, 0x7fffffff, v13
	v_ashrrev_i32_e32 v243, 31, v13
	v_bfi_b32 v13, v243, v13, v242
	v_max_u32_e32 v242, v249, v13
	v_min_u32_e32 v249, v249, v13
	v_min_u32_e32 v137, v137, v242
	v_xor_b32_e32 v244, 0x7fffffff, v14
	v_ashrrev_i32_e32 v245, 31, v14
	v_bfi_b32 v14, v245, v14, v244
	v_max_u32_e32 v244, v150, v14
	v_min_u32_e32 v150, v150, v14
	v_min_u32_e32 v151, v151, v244
	v_xor_b32_e32 v246, 0x7fffffff, v15
	v_ashrrev_i32_e32 v247, 31, v15
	v_bfi_b32 v15, v247, v15, v246
	v_max_u32_e32 v246, v249, v15
	v_min_u32_e32 v249, v249, v15
	v_min_u32_e32 v137, v137, v246
	s_branch .Lsel_cv_next0
.Lsel_cv_slow0:
	v_cmp_lt_i32_e32 vcc, 0, v138
	v_xor_b32_e32 v240, 0x7fffffff, v0
	v_ashrrev_i32_e32 v241, 31, v0
	v_bfi_b32 v0, v241, v0, v240
	v_cndmask_b32_e32 v0, -1, v0, vcc
	v_max_u32_e32 v240, v150, v0
	v_min_u32_e32 v150, v150, v0
	v_min_u32_e32 v151, v151, v240
	v_cmp_lt_i32_e32 vcc, 64, v138
	v_xor_b32_e32 v242, 0x7fffffff, v1
	v_ashrrev_i32_e32 v243, 31, v1
	v_bfi_b32 v1, v243, v1, v242
	v_cndmask_b32_e32 v1, -1, v1, vcc
	v_max_u32_e32 v242, v249, v1
	v_min_u32_e32 v249, v249, v1
	v_min_u32_e32 v137, v137, v242
	v_cmp_lt_i32_e32 vcc, 0x80, v138
	v_xor_b32_e32 v244, 0x7fffffff, v2
	v_ashrrev_i32_e32 v245, 31, v2
	v_bfi_b32 v2, v245, v2, v244
	v_cndmask_b32_e32 v2, -1, v2, vcc
	v_max_u32_e32 v244, v150, v2
	v_min_u32_e32 v150, v150, v2
	v_min_u32_e32 v151, v151, v244
	v_cmp_lt_i32_e32 vcc, 0xc0, v138
	v_xor_b32_e32 v246, 0x7fffffff, v3
	v_ashrrev_i32_e32 v247, 31, v3
	v_bfi_b32 v3, v247, v3, v246
	v_cndmask_b32_e32 v3, -1, v3, vcc
	v_max_u32_e32 v246, v249, v3
	v_min_u32_e32 v249, v249, v3
	v_min_u32_e32 v137, v137, v246
	v_cmp_lt_i32_e32 vcc, 0x100, v138
	v_xor_b32_e32 v240, 0x7fffffff, v4
	v_ashrrev_i32_e32 v241, 31, v4
	v_bfi_b32 v4, v241, v4, v240
	v_cndmask_b32_e32 v4, -1, v4, vcc
	v_max_u32_e32 v240, v150, v4
	v_min_u32_e32 v150, v150, v4
	v_min_u32_e32 v151, v151, v240
	v_cmp_lt_i32_e32 vcc, 0x140, v138
	v_xor_b32_e32 v242, 0x7fffffff, v5
	v_ashrrev_i32_e32 v243, 31, v5
	v_bfi_b32 v5, v243, v5, v242
	v_cndmask_b32_e32 v5, -1, v5, vcc
	v_max_u32_e32 v242, v249, v5
	v_min_u32_e32 v249, v249, v5
	v_min_u32_e32 v137, v137, v242
	v_cmp_lt_i32_e32 vcc, 0x180, v138
	v_xor_b32_e32 v244, 0x7fffffff, v6
	v_ashrrev_i32_e32 v245, 31, v6
	v_bfi_b32 v6, v245, v6, v244
	v_cndmask_b32_e32 v6, -1, v6, vcc
	v_max_u32_e32 v244, v150, v6
	v_min_u32_e32 v150, v150, v6
	v_min_u32_e32 v151, v151, v244
	v_cmp_lt_i32_e32 vcc, 0x1c0, v138
	v_xor_b32_e32 v246, 0x7fffffff, v7
	v_ashrrev_i32_e32 v247, 31, v7
	v_bfi_b32 v7, v247, v7, v246
	v_cndmask_b32_e32 v7, -1, v7, vcc
	v_max_u32_e32 v246, v249, v7
	v_min_u32_e32 v249, v249, v7
	v_min_u32_e32 v137, v137, v246
	v_cmp_lt_i32_e32 vcc, 0x200, v138
	v_xor_b32_e32 v240, 0x7fffffff, v8
	v_ashrrev_i32_e32 v241, 31, v8
	v_bfi_b32 v8, v241, v8, v240
	v_cndmask_b32_e32 v8, -1, v8, vcc
	v_max_u32_e32 v240, v150, v8
	v_min_u32_e32 v150, v150, v8
	v_min_u32_e32 v151, v151, v240
	v_cmp_lt_i32_e32 vcc, 0x240, v138
	v_xor_b32_e32 v242, 0x7fffffff, v9
	v_ashrrev_i32_e32 v243, 31, v9
	v_bfi_b32 v9, v243, v9, v242
	v_cndmask_b32_e32 v9, -1, v9, vcc
	v_max_u32_e32 v242, v249, v9
	v_min_u32_e32 v249, v249, v9
	v_min_u32_e32 v137, v137, v242
	v_cmp_lt_i32_e32 vcc, 0x280, v138
	v_xor_b32_e32 v244, 0x7fffffff, v10
	v_ashrrev_i32_e32 v245, 31, v10
	v_bfi_b32 v10, v245, v10, v244
	v_cndmask_b32_e32 v10, -1, v10, vcc
	v_max_u32_e32 v244, v150, v10
	v_min_u32_e32 v150, v150, v10
	v_min_u32_e32 v151, v151, v244
	v_cmp_lt_i32_e32 vcc, 0x2c0, v138
	v_xor_b32_e32 v246, 0x7fffffff, v11
	v_ashrrev_i32_e32 v247, 31, v11
	v_bfi_b32 v11, v247, v11, v246
	v_cndmask_b32_e32 v11, -1, v11, vcc
	v_max_u32_e32 v246, v249, v11
	v_min_u32_e32 v249, v249, v11
	v_min_u32_e32 v137, v137, v246
	v_cmp_lt_i32_e32 vcc, 0x300, v138
	v_xor_b32_e32 v240, 0x7fffffff, v12
	v_ashrrev_i32_e32 v241, 31, v12
	v_bfi_b32 v12, v241, v12, v240
	v_cndmask_b32_e32 v12, -1, v12, vcc
	v_max_u32_e32 v240, v150, v12
	v_min_u32_e32 v150, v150, v12
	v_min_u32_e32 v151, v151, v240
	v_cmp_lt_i32_e32 vcc, 0x340, v138
	v_xor_b32_e32 v242, 0x7fffffff, v13
	v_ashrrev_i32_e32 v243, 31, v13
	v_bfi_b32 v13, v243, v13, v242
	v_cndmask_b32_e32 v13, -1, v13, vcc
	v_max_u32_e32 v242, v249, v13
	v_min_u32_e32 v249, v249, v13
	v_min_u32_e32 v137, v137, v242
	v_cmp_lt_i32_e32 vcc, 0x380, v138
	v_xor_b32_e32 v244, 0x7fffffff, v14
	v_ashrrev_i32_e32 v245, 31, v14
	v_bfi_b32 v14, v245, v14, v244
	v_cndmask_b32_e32 v14, -1, v14, vcc
	v_max_u32_e32 v244, v150, v14
	v_min_u32_e32 v150, v150, v14
	v_min_u32_e32 v151, v151, v244
	v_cmp_lt_i32_e32 vcc, 0x3c0, v138
	v_xor_b32_e32 v246, 0x7fffffff, v15
	v_ashrrev_i32_e32 v247, 31, v15
	v_bfi_b32 v15, v247, v15, v246
	v_cndmask_b32_e32 v15, -1, v15, vcc
	v_max_u32_e32 v246, v249, v15
	v_min_u32_e32 v249, v249, v15
	v_min_u32_e32 v137, v137, v246
.Lsel_cv_next0:
	s_cmpk_le_u32 s34, 16
	s_cbranch_scc1 .Lsel_cv_done
	s_cmpk_ge_u32 s33, 2048
	s_cbranch_scc0 .Lsel_cv_slow1
	v_xor_b32_e32 v240, 0x7fffffff, v16
	v_ashrrev_i32_e32 v241, 31, v16
	v_bfi_b32 v16, v241, v16, v240
	v_max_u32_e32 v240, v150, v16
	v_min_u32_e32 v150, v150, v16
	v_min_u32_e32 v151, v151, v240
	v_xor_b32_e32 v242, 0x7fffffff, v17
	v_ashrrev_i32_e32 v243, 31, v17
	v_bfi_b32 v17, v243, v17, v242
	v_max_u32_e32 v242, v249, v17
	v_min_u32_e32 v249, v249, v17
	v_min_u32_e32 v137, v137, v242
	v_xor_b32_e32 v244, 0x7fffffff, v18
	v_ashrrev_i32_e32 v245, 31, v18
	v_bfi_b32 v18, v245, v18, v244
	v_max_u32_e32 v244, v150, v18
	v_min_u32_e32 v150, v150, v18
	v_min_u32_e32 v151, v151, v244
	v_xor_b32_e32 v246, 0x7fffffff, v19
	v_ashrrev_i32_e32 v247, 31, v19
	v_bfi_b32 v19, v247, v19, v246
	v_max_u32_e32 v246, v249, v19
	v_min_u32_e32 v249, v249, v19
	v_min_u32_e32 v137, v137, v246
	v_xor_b32_e32 v240, 0x7fffffff, v20
	v_ashrrev_i32_e32 v241, 31, v20
	v_bfi_b32 v20, v241, v20, v240
	v_max_u32_e32 v240, v150, v20
	v_min_u32_e32 v150, v150, v20
	v_min_u32_e32 v151, v151, v240
	v_xor_b32_e32 v242, 0x7fffffff, v21
	v_ashrrev_i32_e32 v243, 31, v21
	v_bfi_b32 v21, v243, v21, v242
	v_max_u32_e32 v242, v249, v21
	v_min_u32_e32 v249, v249, v21
	v_min_u32_e32 v137, v137, v242
	v_xor_b32_e32 v244, 0x7fffffff, v22
	v_ashrrev_i32_e32 v245, 31, v22
	v_bfi_b32 v22, v245, v22, v244
	v_max_u32_e32 v244, v150, v22
	v_min_u32_e32 v150, v150, v22
	v_min_u32_e32 v151, v151, v244
	v_xor_b32_e32 v246, 0x7fffffff, v23
	v_ashrrev_i32_e32 v247, 31, v23
	v_bfi_b32 v23, v247, v23, v246
	v_max_u32_e32 v246, v249, v23
	v_min_u32_e32 v249, v249, v23
	v_min_u32_e32 v137, v137, v246
	v_xor_b32_e32 v240, 0x7fffffff, v24
	v_ashrrev_i32_e32 v241, 31, v24
	v_bfi_b32 v24, v241, v24, v240
	v_max_u32_e32 v240, v150, v24
	v_min_u32_e32 v150, v150, v24
	v_min_u32_e32 v151, v151, v240
	v_xor_b32_e32 v242, 0x7fffffff, v25
	v_ashrrev_i32_e32 v243, 31, v25
	v_bfi_b32 v25, v243, v25, v242
	v_max_u32_e32 v242, v249, v25
	v_min_u32_e32 v249, v249, v25
	v_min_u32_e32 v137, v137, v242
	v_xor_b32_e32 v244, 0x7fffffff, v26
	v_ashrrev_i32_e32 v245, 31, v26
	v_bfi_b32 v26, v245, v26, v244
	v_max_u32_e32 v244, v150, v26
	v_min_u32_e32 v150, v150, v26
	v_min_u32_e32 v151, v151, v244
	v_xor_b32_e32 v246, 0x7fffffff, v27
	v_ashrrev_i32_e32 v247, 31, v27
	v_bfi_b32 v27, v247, v27, v246
	v_max_u32_e32 v246, v249, v27
	v_min_u32_e32 v249, v249, v27
	v_min_u32_e32 v137, v137, v246
	v_xor_b32_e32 v240, 0x7fffffff, v28
	v_ashrrev_i32_e32 v241, 31, v28
	v_bfi_b32 v28, v241, v28, v240
	v_max_u32_e32 v240, v150, v28
	v_min_u32_e32 v150, v150, v28
	v_min_u32_e32 v151, v151, v240
	v_xor_b32_e32 v242, 0x7fffffff, v29
	v_ashrrev_i32_e32 v243, 31, v29
	v_bfi_b32 v29, v243, v29, v242
	v_max_u32_e32 v242, v249, v29
	v_min_u32_e32 v249, v249, v29
	v_min_u32_e32 v137, v137, v242
	v_xor_b32_e32 v244, 0x7fffffff, v30
	v_ashrrev_i32_e32 v245, 31, v30
	v_bfi_b32 v30, v245, v30, v244
	v_max_u32_e32 v244, v150, v30
	v_min_u32_e32 v150, v150, v30
	v_min_u32_e32 v151, v151, v244
	v_xor_b32_e32 v246, 0x7fffffff, v31
	v_ashrrev_i32_e32 v247, 31, v31
	v_bfi_b32 v31, v247, v31, v246
	v_max_u32_e32 v246, v249, v31
	v_min_u32_e32 v249, v249, v31
	v_min_u32_e32 v137, v137, v246
	s_branch .Lsel_cv_next1
.Lsel_cv_slow1:
	v_cmp_lt_i32_e32 vcc, 0x400, v138
	v_xor_b32_e32 v240, 0x7fffffff, v16
	v_ashrrev_i32_e32 v241, 31, v16
	v_bfi_b32 v16, v241, v16, v240
	v_cndmask_b32_e32 v16, -1, v16, vcc
	v_max_u32_e32 v240, v150, v16
	v_min_u32_e32 v150, v150, v16
	v_min_u32_e32 v151, v151, v240
	v_cmp_lt_i32_e32 vcc, 0x440, v138
	v_xor_b32_e32 v242, 0x7fffffff, v17
	v_ashrrev_i32_e32 v243, 31, v17
	v_bfi_b32 v17, v243, v17, v242
	v_cndmask_b32_e32 v17, -1, v17, vcc
	v_max_u32_e32 v242, v249, v17
	v_min_u32_e32 v249, v249, v17
	v_min_u32_e32 v137, v137, v242
	v_cmp_lt_i32_e32 vcc, 0x480, v138
	v_xor_b32_e32 v244, 0x7fffffff, v18
	v_ashrrev_i32_e32 v245, 31, v18
	v_bfi_b32 v18, v245, v18, v244
	v_cndmask_b32_e32 v18, -1, v18, vcc
	v_max_u32_e32 v244, v150, v18
	v_min_u32_e32 v150, v150, v18
	v_min_u32_e32 v151, v151, v244
	v_cmp_lt_i32_e32 vcc, 0x4c0, v138
	v_xor_b32_e32 v246, 0x7fffffff, v19
	v_ashrrev_i32_e32 v247, 31, v19
	v_bfi_b32 v19, v247, v19, v246
	v_cndmask_b32_e32 v19, -1, v19, vcc
	v_max_u32_e32 v246, v249, v19
	v_min_u32_e32 v249, v249, v19
	v_min_u32_e32 v137, v137, v246
	v_cmp_lt_i32_e32 vcc, 0x500, v138
	v_xor_b32_e32 v240, 0x7fffffff, v20
	v_ashrrev_i32_e32 v241, 31, v20
	v_bfi_b32 v20, v241, v20, v240
	v_cndmask_b32_e32 v20, -1, v20, vcc
	v_max_u32_e32 v240, v150, v20
	v_min_u32_e32 v150, v150, v20
	v_min_u32_e32 v151, v151, v240
	v_cmp_lt_i32_e32 vcc, 0x540, v138
	v_xor_b32_e32 v242, 0x7fffffff, v21
	v_ashrrev_i32_e32 v243, 31, v21
	v_bfi_b32 v21, v243, v21, v242
	v_cndmask_b32_e32 v21, -1, v21, vcc
	v_max_u32_e32 v242, v249, v21
	v_min_u32_e32 v249, v249, v21
	v_min_u32_e32 v137, v137, v242
	v_cmp_lt_i32_e32 vcc, 0x580, v138
	v_xor_b32_e32 v244, 0x7fffffff, v22
	v_ashrrev_i32_e32 v245, 31, v22
	v_bfi_b32 v22, v245, v22, v244
	v_cndmask_b32_e32 v22, -1, v22, vcc
	v_max_u32_e32 v244, v150, v22
	v_min_u32_e32 v150, v150, v22
	v_min_u32_e32 v151, v151, v244
	v_cmp_lt_i32_e32 vcc, 0x5c0, v138
	v_xor_b32_e32 v246, 0x7fffffff, v23
	v_ashrrev_i32_e32 v247, 31, v23
	v_bfi_b32 v23, v247, v23, v246
	v_cndmask_b32_e32 v23, -1, v23, vcc
	v_max_u32_e32 v246, v249, v23
	v_min_u32_e32 v249, v249, v23
	v_min_u32_e32 v137, v137, v246
	v_cmp_lt_i32_e32 vcc, 0x600, v138
	v_xor_b32_e32 v240, 0x7fffffff, v24
	v_ashrrev_i32_e32 v241, 31, v24
	v_bfi_b32 v24, v241, v24, v240
	v_cndmask_b32_e32 v24, -1, v24, vcc
	v_max_u32_e32 v240, v150, v24
	v_min_u32_e32 v150, v150, v24
	v_min_u32_e32 v151, v151, v240
	v_cmp_lt_i32_e32 vcc, 0x640, v138
	v_xor_b32_e32 v242, 0x7fffffff, v25
	v_ashrrev_i32_e32 v243, 31, v25
	v_bfi_b32 v25, v243, v25, v242
	v_cndmask_b32_e32 v25, -1, v25, vcc
	v_max_u32_e32 v242, v249, v25
	v_min_u32_e32 v249, v249, v25
	v_min_u32_e32 v137, v137, v242
	v_cmp_lt_i32_e32 vcc, 0x680, v138
	v_xor_b32_e32 v244, 0x7fffffff, v26
	v_ashrrev_i32_e32 v245, 31, v26
	v_bfi_b32 v26, v245, v26, v244
	v_cndmask_b32_e32 v26, -1, v26, vcc
	v_max_u32_e32 v244, v150, v26
	v_min_u32_e32 v150, v150, v26
	v_min_u32_e32 v151, v151, v244
	v_cmp_lt_i32_e32 vcc, 0x6c0, v138
	v_xor_b32_e32 v246, 0x7fffffff, v27
	v_ashrrev_i32_e32 v247, 31, v27
	v_bfi_b32 v27, v247, v27, v246
	v_cndmask_b32_e32 v27, -1, v27, vcc
	v_max_u32_e32 v246, v249, v27
	v_min_u32_e32 v249, v249, v27
	v_min_u32_e32 v137, v137, v246
	v_cmp_lt_i32_e32 vcc, 0x700, v138
	v_xor_b32_e32 v240, 0x7fffffff, v28
	v_ashrrev_i32_e32 v241, 31, v28
	v_bfi_b32 v28, v241, v28, v240
	v_cndmask_b32_e32 v28, -1, v28, vcc
	v_max_u32_e32 v240, v150, v28
	v_min_u32_e32 v150, v150, v28
	v_min_u32_e32 v151, v151, v240
	v_cmp_lt_i32_e32 vcc, 0x740, v138
	v_xor_b32_e32 v242, 0x7fffffff, v29
	v_ashrrev_i32_e32 v243, 31, v29
	v_bfi_b32 v29, v243, v29, v242
	v_cndmask_b32_e32 v29, -1, v29, vcc
	v_max_u32_e32 v242, v249, v29
	v_min_u32_e32 v249, v249, v29
	v_min_u32_e32 v137, v137, v242
	v_cmp_lt_i32_e32 vcc, 0x780, v138
	v_xor_b32_e32 v244, 0x7fffffff, v30
	v_ashrrev_i32_e32 v245, 31, v30
	v_bfi_b32 v30, v245, v30, v244
	v_cndmask_b32_e32 v30, -1, v30, vcc
	v_max_u32_e32 v244, v150, v30
	v_min_u32_e32 v150, v150, v30
	v_min_u32_e32 v151, v151, v244
	v_cmp_lt_i32_e32 vcc, 0x7c0, v138
	v_xor_b32_e32 v246, 0x7fffffff, v31
	v_ashrrev_i32_e32 v247, 31, v31
	v_bfi_b32 v31, v247, v31, v246
	v_cndmask_b32_e32 v31, -1, v31, vcc
	v_max_u32_e32 v246, v249, v31
	v_min_u32_e32 v249, v249, v31
	v_min_u32_e32 v137, v137, v246
.Lsel_cv_next1:
	s_cmpk_le_u32 s34, 32
	s_cbranch_scc1 .Lsel_cv_done
	s_cmpk_ge_u32 s33, 3072
	s_cbranch_scc0 .Lsel_cv_slow2
	v_xor_b32_e32 v240, 0x7fffffff, v32
	v_ashrrev_i32_e32 v241, 31, v32
	v_bfi_b32 v32, v241, v32, v240
	v_max_u32_e32 v240, v150, v32
	v_min_u32_e32 v150, v150, v32
	v_min_u32_e32 v151, v151, v240
	v_xor_b32_e32 v242, 0x7fffffff, v33
	v_ashrrev_i32_e32 v243, 31, v33
	v_bfi_b32 v33, v243, v33, v242
	v_max_u32_e32 v242, v249, v33
	v_min_u32_e32 v249, v249, v33
	v_min_u32_e32 v137, v137, v242
	v_xor_b32_e32 v244, 0x7fffffff, v34
	v_ashrrev_i32_e32 v245, 31, v34
	v_bfi_b32 v34, v245, v34, v244
	v_max_u32_e32 v244, v150, v34
	v_min_u32_e32 v150, v150, v34
	v_min_u32_e32 v151, v151, v244
	v_xor_b32_e32 v246, 0x7fffffff, v35
	v_ashrrev_i32_e32 v247, 31, v35
	v_bfi_b32 v35, v247, v35, v246
	v_max_u32_e32 v246, v249, v35
	v_min_u32_e32 v249, v249, v35
	v_min_u32_e32 v137, v137, v246
	v_xor_b32_e32 v240, 0x7fffffff, v36
	v_ashrrev_i32_e32 v241, 31, v36
	v_bfi_b32 v36, v241, v36, v240
	v_max_u32_e32 v240, v150, v36
	v_min_u32_e32 v150, v150, v36
	v_min_u32_e32 v151, v151, v240
	v_xor_b32_e32 v242, 0x7fffffff, v37
	v_ashrrev_i32_e32 v243, 31, v37
	v_bfi_b32 v37, v243, v37, v242
	v_max_u32_e32 v242, v249, v37
	v_min_u32_e32 v249, v249, v37
	v_min_u32_e32 v137, v137, v242
	v_xor_b32_e32 v244, 0x7fffffff, v38
	v_ashrrev_i32_e32 v245, 31, v38
	v_bfi_b32 v38, v245, v38, v244
	v_max_u32_e32 v244, v150, v38
	v_min_u32_e32 v150, v150, v38
	v_min_u32_e32 v151, v151, v244
	v_xor_b32_e32 v246, 0x7fffffff, v39
	v_ashrrev_i32_e32 v247, 31, v39
	v_bfi_b32 v39, v247, v39, v246
	v_max_u32_e32 v246, v249, v39
	v_min_u32_e32 v249, v249, v39
	v_min_u32_e32 v137, v137, v246
	v_xor_b32_e32 v240, 0x7fffffff, v40
	v_ashrrev_i32_e32 v241, 31, v40
	v_bfi_b32 v40, v241, v40, v240
	v_max_u32_e32 v240, v150, v40
	v_min_u32_e32 v150, v150, v40
	v_min_u32_e32 v151, v151, v240
	v_xor_b32_e32 v242, 0x7fffffff, v41
	v_ashrrev_i32_e32 v243, 31, v41
	v_bfi_b32 v41, v243, v41, v242
	v_max_u32_e32 v242, v249, v41
	v_min_u32_e32 v249, v249, v41
	v_min_u32_e32 v137, v137, v242
	v_xor_b32_e32 v244, 0x7fffffff, v42
	v_ashrrev_i32_e32 v245, 31, v42
	v_bfi_b32 v42, v245, v42, v244
	v_max_u32_e32 v244, v150, v42
	v_min_u32_e32 v150, v150, v42
	v_min_u32_e32 v151, v151, v244
	v_xor_b32_e32 v246, 0x7fffffff, v43
	v_ashrrev_i32_e32 v247, 31, v43
	v_bfi_b32 v43, v247, v43, v246
	v_max_u32_e32 v246, v249, v43
	v_min_u32_e32 v249, v249, v43
	v_min_u32_e32 v137, v137, v246
	v_xor_b32_e32 v240, 0x7fffffff, v44
	v_ashrrev_i32_e32 v241, 31, v44
	v_bfi_b32 v44, v241, v44, v240
	v_max_u32_e32 v240, v150, v44
	v_min_u32_e32 v150, v150, v44
	v_min_u32_e32 v151, v151, v240
	v_xor_b32_e32 v242, 0x7fffffff, v45
	v_ashrrev_i32_e32 v243, 31, v45
	v_bfi_b32 v45, v243, v45, v242
	v_max_u32_e32 v242, v249, v45
	v_min_u32_e32 v249, v249, v45
	v_min_u32_e32 v137, v137, v242
	v_xor_b32_e32 v244, 0x7fffffff, v46
	v_ashrrev_i32_e32 v245, 31, v46
	v_bfi_b32 v46, v245, v46, v244
	v_max_u32_e32 v244, v150, v46
	v_min_u32_e32 v150, v150, v46
	v_min_u32_e32 v151, v151, v244
	v_xor_b32_e32 v246, 0x7fffffff, v47
	v_ashrrev_i32_e32 v247, 31, v47
	v_bfi_b32 v47, v247, v47, v246
	v_max_u32_e32 v246, v249, v47
	v_min_u32_e32 v249, v249, v47
	v_min_u32_e32 v137, v137, v246
	s_branch .Lsel_cv_next2
.Lsel_cv_slow2:
	v_cmp_lt_i32_e32 vcc, 0x800, v138
	v_xor_b32_e32 v240, 0x7fffffff, v32
	v_ashrrev_i32_e32 v241, 31, v32
	v_bfi_b32 v32, v241, v32, v240
	v_cndmask_b32_e32 v32, -1, v32, vcc
	v_max_u32_e32 v240, v150, v32
	v_min_u32_e32 v150, v150, v32
	v_min_u32_e32 v151, v151, v240
	v_cmp_lt_i32_e32 vcc, 0x840, v138
	v_xor_b32_e32 v242, 0x7fffffff, v33
	v_ashrrev_i32_e32 v243, 31, v33
	v_bfi_b32 v33, v243, v33, v242
	v_cndmask_b32_e32 v33, -1, v33, vcc
	v_max_u32_e32 v242, v249, v33
	v_min_u32_e32 v249, v249, v33
	v_min_u32_e32 v137, v137, v242
	v_cmp_lt_i32_e32 vcc, 0x880, v138
	v_xor_b32_e32 v244, 0x7fffffff, v34
	v_ashrrev_i32_e32 v245, 31, v34
	v_bfi_b32 v34, v245, v34, v244
	v_cndmask_b32_e32 v34, -1, v34, vcc
	v_max_u32_e32 v244, v150, v34
	v_min_u32_e32 v150, v150, v34
	v_min_u32_e32 v151, v151, v244
	v_cmp_lt_i32_e32 vcc, 0x8c0, v138
	v_xor_b32_e32 v246, 0x7fffffff, v35
	v_ashrrev_i32_e32 v247, 31, v35
	v_bfi_b32 v35, v247, v35, v246
	v_cndmask_b32_e32 v35, -1, v35, vcc
	v_max_u32_e32 v246, v249, v35
	v_min_u32_e32 v249, v249, v35
	v_min_u32_e32 v137, v137, v246
	v_cmp_lt_i32_e32 vcc, 0x900, v138
	v_xor_b32_e32 v240, 0x7fffffff, v36
	v_ashrrev_i32_e32 v241, 31, v36
	v_bfi_b32 v36, v241, v36, v240
	v_cndmask_b32_e32 v36, -1, v36, vcc
	v_max_u32_e32 v240, v150, v36
	v_min_u32_e32 v150, v150, v36
	v_min_u32_e32 v151, v151, v240
	v_cmp_lt_i32_e32 vcc, 0x940, v138
	v_xor_b32_e32 v242, 0x7fffffff, v37
	v_ashrrev_i32_e32 v243, 31, v37
	v_bfi_b32 v37, v243, v37, v242
	v_cndmask_b32_e32 v37, -1, v37, vcc
	v_max_u32_e32 v242, v249, v37
	v_min_u32_e32 v249, v249, v37
	v_min_u32_e32 v137, v137, v242
	v_cmp_lt_i32_e32 vcc, 0x980, v138
	v_xor_b32_e32 v244, 0x7fffffff, v38
	v_ashrrev_i32_e32 v245, 31, v38
	v_bfi_b32 v38, v245, v38, v244
	v_cndmask_b32_e32 v38, -1, v38, vcc
	v_max_u32_e32 v244, v150, v38
	v_min_u32_e32 v150, v150, v38
	v_min_u32_e32 v151, v151, v244
	v_cmp_lt_i32_e32 vcc, 0x9c0, v138
	v_xor_b32_e32 v246, 0x7fffffff, v39
	v_ashrrev_i32_e32 v247, 31, v39
	v_bfi_b32 v39, v247, v39, v246
	v_cndmask_b32_e32 v39, -1, v39, vcc
	v_max_u32_e32 v246, v249, v39
	v_min_u32_e32 v249, v249, v39
	v_min_u32_e32 v137, v137, v246
	v_cmp_lt_i32_e32 vcc, 0xa00, v138
	v_xor_b32_e32 v240, 0x7fffffff, v40
	v_ashrrev_i32_e32 v241, 31, v40
	v_bfi_b32 v40, v241, v40, v240
	v_cndmask_b32_e32 v40, -1, v40, vcc
	v_max_u32_e32 v240, v150, v40
	v_min_u32_e32 v150, v150, v40
	v_min_u32_e32 v151, v151, v240
	v_cmp_lt_i32_e32 vcc, 0xa40, v138
	v_xor_b32_e32 v242, 0x7fffffff, v41
	v_ashrrev_i32_e32 v243, 31, v41
	v_bfi_b32 v41, v243, v41, v242
	v_cndmask_b32_e32 v41, -1, v41, vcc
	v_max_u32_e32 v242, v249, v41
	v_min_u32_e32 v249, v249, v41
	v_min_u32_e32 v137, v137, v242
	v_cmp_lt_i32_e32 vcc, 0xa80, v138
	v_xor_b32_e32 v244, 0x7fffffff, v42
	v_ashrrev_i32_e32 v245, 31, v42
	v_bfi_b32 v42, v245, v42, v244
	v_cndmask_b32_e32 v42, -1, v42, vcc
	v_max_u32_e32 v244, v150, v42
	v_min_u32_e32 v150, v150, v42
	v_min_u32_e32 v151, v151, v244
	v_cmp_lt_i32_e32 vcc, 0xac0, v138
	v_xor_b32_e32 v246, 0x7fffffff, v43
	v_ashrrev_i32_e32 v247, 31, v43
	v_bfi_b32 v43, v247, v43, v246
	v_cndmask_b32_e32 v43, -1, v43, vcc
	v_max_u32_e32 v246, v249, v43
	v_min_u32_e32 v249, v249, v43
	v_min_u32_e32 v137, v137, v246
	v_cmp_lt_i32_e32 vcc, 0xb00, v138
	v_xor_b32_e32 v240, 0x7fffffff, v44
	v_ashrrev_i32_e32 v241, 31, v44
	v_bfi_b32 v44, v241, v44, v240
	v_cndmask_b32_e32 v44, -1, v44, vcc
	v_max_u32_e32 v240, v150, v44
	v_min_u32_e32 v150, v150, v44
	v_min_u32_e32 v151, v151, v240
	v_cmp_lt_i32_e32 vcc, 0xb40, v138
	v_xor_b32_e32 v242, 0x7fffffff, v45
	v_ashrrev_i32_e32 v243, 31, v45
	v_bfi_b32 v45, v243, v45, v242
	v_cndmask_b32_e32 v45, -1, v45, vcc
	v_max_u32_e32 v242, v249, v45
	v_min_u32_e32 v249, v249, v45
	v_min_u32_e32 v137, v137, v242
	v_cmp_lt_i32_e32 vcc, 0xb80, v138
	v_xor_b32_e32 v244, 0x7fffffff, v46
	v_ashrrev_i32_e32 v245, 31, v46
	v_bfi_b32 v46, v245, v46, v244
	v_cndmask_b32_e32 v46, -1, v46, vcc
	v_max_u32_e32 v244, v150, v46
	v_min_u32_e32 v150, v150, v46
	v_min_u32_e32 v151, v151, v244
	v_cmp_lt_i32_e32 vcc, 0xbc0, v138
	v_xor_b32_e32 v246, 0x7fffffff, v47
	v_ashrrev_i32_e32 v247, 31, v47
	v_bfi_b32 v47, v247, v47, v246
	v_cndmask_b32_e32 v47, -1, v47, vcc
	v_max_u32_e32 v246, v249, v47
	v_min_u32_e32 v249, v249, v47
	v_min_u32_e32 v137, v137, v246
.Lsel_cv_next2:
	s_cmpk_le_u32 s34, 48
	s_cbranch_scc1 .Lsel_cv_done
	s_cmpk_ge_u32 s33, 4096
	s_cbranch_scc0 .Lsel_cv_slow3
	v_xor_b32_e32 v240, 0x7fffffff, v48
	v_ashrrev_i32_e32 v241, 31, v48
	v_bfi_b32 v48, v241, v48, v240
	v_max_u32_e32 v240, v150, v48
	v_min_u32_e32 v150, v150, v48
	v_min_u32_e32 v151, v151, v240
	v_xor_b32_e32 v242, 0x7fffffff, v49
	v_ashrrev_i32_e32 v243, 31, v49
	v_bfi_b32 v49, v243, v49, v242
	v_max_u32_e32 v242, v249, v49
	v_min_u32_e32 v249, v249, v49
	v_min_u32_e32 v137, v137, v242
	v_xor_b32_e32 v244, 0x7fffffff, v50
	v_ashrrev_i32_e32 v245, 31, v50
	v_bfi_b32 v50, v245, v50, v244
	v_max_u32_e32 v244, v150, v50
	v_min_u32_e32 v150, v150, v50
	v_min_u32_e32 v151, v151, v244
	v_xor_b32_e32 v246, 0x7fffffff, v51
	v_ashrrev_i32_e32 v247, 31, v51
	v_bfi_b32 v51, v247, v51, v246
	v_max_u32_e32 v246, v249, v51
	v_min_u32_e32 v249, v249, v51
	v_min_u32_e32 v137, v137, v246
	v_xor_b32_e32 v240, 0x7fffffff, v52
	v_ashrrev_i32_e32 v241, 31, v52
	v_bfi_b32 v52, v241, v52, v240
	v_max_u32_e32 v240, v150, v52
	v_min_u32_e32 v150, v150, v52
	v_min_u32_e32 v151, v151, v240
	v_xor_b32_e32 v242, 0x7fffffff, v53
	v_ashrrev_i32_e32 v243, 31, v53
	v_bfi_b32 v53, v243, v53, v242
	v_max_u32_e32 v242, v249, v53
	v_min_u32_e32 v249, v249, v53
	v_min_u32_e32 v137, v137, v242
	v_xor_b32_e32 v244, 0x7fffffff, v54
	v_ashrrev_i32_e32 v245, 31, v54
	v_bfi_b32 v54, v245, v54, v244
	v_max_u32_e32 v244, v150, v54
	v_min_u32_e32 v150, v150, v54
	v_min_u32_e32 v151, v151, v244
	v_xor_b32_e32 v246, 0x7fffffff, v55
	v_ashrrev_i32_e32 v247, 31, v55
	v_bfi_b32 v55, v247, v55, v246
	v_max_u32_e32 v246, v249, v55
	v_min_u32_e32 v249, v249, v55
	v_min_u32_e32 v137, v137, v246
	v_xor_b32_e32 v240, 0x7fffffff, v56
	v_ashrrev_i32_e32 v241, 31, v56
	v_bfi_b32 v56, v241, v56, v240
	v_max_u32_e32 v240, v150, v56
	v_min_u32_e32 v150, v150, v56
	v_min_u32_e32 v151, v151, v240
	v_xor_b32_e32 v242, 0x7fffffff, v57
	v_ashrrev_i32_e32 v243, 31, v57
	v_bfi_b32 v57, v243, v57, v242
	v_max_u32_e32 v242, v249, v57
	v_min_u32_e32 v249, v249, v57
	v_min_u32_e32 v137, v137, v242
	v_xor_b32_e32 v244, 0x7fffffff, v58
	v_ashrrev_i32_e32 v245, 31, v58
	v_bfi_b32 v58, v245, v58, v244
	v_max_u32_e32 v244, v150, v58
	v_min_u32_e32 v150, v150, v58
	v_min_u32_e32 v151, v151, v244
	v_xor_b32_e32 v246, 0x7fffffff, v59
	v_ashrrev_i32_e32 v247, 31, v59
	v_bfi_b32 v59, v247, v59, v246
	v_max_u32_e32 v246, v249, v59
	v_min_u32_e32 v249, v249, v59
	v_min_u32_e32 v137, v137, v246
	v_xor_b32_e32 v240, 0x7fffffff, v60
	v_ashrrev_i32_e32 v241, 31, v60
	v_bfi_b32 v60, v241, v60, v240
	v_max_u32_e32 v240, v150, v60
	v_min_u32_e32 v150, v150, v60
	v_min_u32_e32 v151, v151, v240
	v_xor_b32_e32 v242, 0x7fffffff, v61
	v_ashrrev_i32_e32 v243, 31, v61
	v_bfi_b32 v61, v243, v61, v242
	v_max_u32_e32 v242, v249, v61
	v_min_u32_e32 v249, v249, v61
	v_min_u32_e32 v137, v137, v242
	v_xor_b32_e32 v244, 0x7fffffff, v62
	v_ashrrev_i32_e32 v245, 31, v62
	v_bfi_b32 v62, v245, v62, v244
	v_max_u32_e32 v244, v150, v62
	v_min_u32_e32 v150, v150, v62
	v_min_u32_e32 v151, v151, v244
	v_xor_b32_e32 v246, 0x7fffffff, v63
	v_ashrrev_i32_e32 v247, 31, v63
	v_bfi_b32 v63, v247, v63, v246
	v_max_u32_e32 v246, v249, v63
	v_min_u32_e32 v249, v249, v63
	v_min_u32_e32 v137, v137, v246
	s_branch .Lsel_cv_next3
.Lsel_cv_slow3:
	v_cmp_lt_i32_e32 vcc, 0xc00, v138
	v_xor_b32_e32 v240, 0x7fffffff, v48
	v_ashrrev_i32_e32 v241, 31, v48
	v_bfi_b32 v48, v241, v48, v240
	v_cndmask_b32_e32 v48, -1, v48, vcc
	v_max_u32_e32 v240, v150, v48
	v_min_u32_e32 v150, v150, v48
	v_min_u32_e32 v151, v151, v240
	v_cmp_lt_i32_e32 vcc, 0xc40, v138
	v_xor_b32_e32 v242, 0x7fffffff, v49
	v_ashrrev_i32_e32 v243, 31, v49
	v_bfi_b32 v49, v243, v49, v242
	v_cndmask_b32_e32 v49, -1, v49, vcc
	v_max_u32_e32 v242, v249, v49
	v_min_u32_e32 v249, v249, v49
	v_min_u32_e32 v137, v137, v242
	v_cmp_lt_i32_e32 vcc, 0xc80, v138
	v_xor_b32_e32 v244, 0x7fffffff, v50
	v_ashrrev_i32_e32 v245, 31, v50
	v_bfi_b32 v50, v245, v50, v244
	v_cndmask_b32_e32 v50, -1, v50, vcc
	v_max_u32_e32 v244, v150, v50
	v_min_u32_e32 v150, v150, v50
	v_min_u32_e32 v151, v151, v244
	v_cmp_lt_i32_e32 vcc, 0xcc0, v138
	v_xor_b32_e32 v246, 0x7fffffff, v51
	v_ashrrev_i32_e32 v247, 31, v51
	v_bfi_b32 v51, v247, v51, v246
	v_cndmask_b32_e32 v51, -1, v51, vcc
	v_max_u32_e32 v246, v249, v51
	v_min_u32_e32 v249, v249, v51
	v_min_u32_e32 v137, v137, v246
	v_cmp_lt_i32_e32 vcc, 0xd00, v138
	v_xor_b32_e32 v240, 0x7fffffff, v52
	v_ashrrev_i32_e32 v241, 31, v52
	v_bfi_b32 v52, v241, v52, v240
	v_cndmask_b32_e32 v52, -1, v52, vcc
	v_max_u32_e32 v240, v150, v52
	v_min_u32_e32 v150, v150, v52
	v_min_u32_e32 v151, v151, v240
	v_cmp_lt_i32_e32 vcc, 0xd40, v138
	v_xor_b32_e32 v242, 0x7fffffff, v53
	v_ashrrev_i32_e32 v243, 31, v53
	v_bfi_b32 v53, v243, v53, v242
	v_cndmask_b32_e32 v53, -1, v53, vcc
	v_max_u32_e32 v242, v249, v53
	v_min_u32_e32 v249, v249, v53
	v_min_u32_e32 v137, v137, v242
	v_cmp_lt_i32_e32 vcc, 0xd80, v138
	v_xor_b32_e32 v244, 0x7fffffff, v54
	v_ashrrev_i32_e32 v245, 31, v54
	v_bfi_b32 v54, v245, v54, v244
	v_cndmask_b32_e32 v54, -1, v54, vcc
	v_max_u32_e32 v244, v150, v54
	v_min_u32_e32 v150, v150, v54
	v_min_u32_e32 v151, v151, v244
	v_cmp_lt_i32_e32 vcc, 0xdc0, v138
	v_xor_b32_e32 v246, 0x7fffffff, v55
	v_ashrrev_i32_e32 v247, 31, v55
	v_bfi_b32 v55, v247, v55, v246
	v_cndmask_b32_e32 v55, -1, v55, vcc
	v_max_u32_e32 v246, v249, v55
	v_min_u32_e32 v249, v249, v55
	v_min_u32_e32 v137, v137, v246
	v_cmp_lt_i32_e32 vcc, 0xe00, v138
	v_xor_b32_e32 v240, 0x7fffffff, v56
	v_ashrrev_i32_e32 v241, 31, v56
	v_bfi_b32 v56, v241, v56, v240
	v_cndmask_b32_e32 v56, -1, v56, vcc
	v_max_u32_e32 v240, v150, v56
	v_min_u32_e32 v150, v150, v56
	v_min_u32_e32 v151, v151, v240
	v_cmp_lt_i32_e32 vcc, 0xe40, v138
	v_xor_b32_e32 v242, 0x7fffffff, v57
	v_ashrrev_i32_e32 v243, 31, v57
	v_bfi_b32 v57, v243, v57, v242
	v_cndmask_b32_e32 v57, -1, v57, vcc
	v_max_u32_e32 v242, v249, v57
	v_min_u32_e32 v249, v249, v57
	v_min_u32_e32 v137, v137, v242
	v_cmp_lt_i32_e32 vcc, 0xe80, v138
	v_xor_b32_e32 v244, 0x7fffffff, v58
	v_ashrrev_i32_e32 v245, 31, v58
	v_bfi_b32 v58, v245, v58, v244
	v_cndmask_b32_e32 v58, -1, v58, vcc
	v_max_u32_e32 v244, v150, v58
	v_min_u32_e32 v150, v150, v58
	v_min_u32_e32 v151, v151, v244
	v_cmp_lt_i32_e32 vcc, 0xec0, v138
	v_xor_b32_e32 v246, 0x7fffffff, v59
	v_ashrrev_i32_e32 v247, 31, v59
	v_bfi_b32 v59, v247, v59, v246
	v_cndmask_b32_e32 v59, -1, v59, vcc
	v_max_u32_e32 v246, v249, v59
	v_min_u32_e32 v249, v249, v59
	v_min_u32_e32 v137, v137, v246
	v_cmp_lt_i32_e32 vcc, 0xf00, v138
	v_xor_b32_e32 v240, 0x7fffffff, v60
	v_ashrrev_i32_e32 v241, 31, v60
	v_bfi_b32 v60, v241, v60, v240
	v_cndmask_b32_e32 v60, -1, v60, vcc
	v_max_u32_e32 v240, v150, v60
	v_min_u32_e32 v150, v150, v60
	v_min_u32_e32 v151, v151, v240
	v_cmp_lt_i32_e32 vcc, 0xf40, v138
	v_xor_b32_e32 v242, 0x7fffffff, v61
	v_ashrrev_i32_e32 v243, 31, v61
	v_bfi_b32 v61, v243, v61, v242
	v_cndmask_b32_e32 v61, -1, v61, vcc
	v_max_u32_e32 v242, v249, v61
	v_min_u32_e32 v249, v249, v61
	v_min_u32_e32 v137, v137, v242
	v_cmp_lt_i32_e32 vcc, 0xf80, v138
	v_xor_b32_e32 v244, 0x7fffffff, v62
	v_ashrrev_i32_e32 v245, 31, v62
	v_bfi_b32 v62, v245, v62, v244
	v_cndmask_b32_e32 v62, -1, v62, vcc
	v_max_u32_e32 v244, v150, v62
	v_min_u32_e32 v150, v150, v62
	v_min_u32_e32 v151, v151, v244
	v_cmp_lt_i32_e32 vcc, 0xfc0, v138
	v_xor_b32_e32 v246, 0x7fffffff, v63
	v_ashrrev_i32_e32 v247, 31, v63
	v_bfi_b32 v63, v247, v63, v246
	v_cndmask_b32_e32 v63, -1, v63, vcc
	v_max_u32_e32 v246, v249, v63
	v_min_u32_e32 v249, v249, v63
	v_min_u32_e32 v137, v137, v246
.Lsel_cv_next3:
	s_cmpk_le_u32 s34, 64
	s_cbranch_scc1 .Lsel_cv_done
	s_cmpk_ge_u32 s33, 5120
	s_cbranch_scc0 .Lsel_cv_slow4
	v_xor_b32_e32 v240, 0x7fffffff, v64
	v_ashrrev_i32_e32 v241, 31, v64
	v_bfi_b32 v64, v241, v64, v240
	v_max_u32_e32 v240, v150, v64
	v_min_u32_e32 v150, v150, v64
	v_min_u32_e32 v151, v151, v240
	v_xor_b32_e32 v242, 0x7fffffff, v65
	v_ashrrev_i32_e32 v243, 31, v65
	v_bfi_b32 v65, v243, v65, v242
	v_max_u32_e32 v242, v249, v65
	v_min_u32_e32 v249, v249, v65
	v_min_u32_e32 v137, v137, v242
	v_xor_b32_e32 v244, 0x7fffffff, v66
	v_ashrrev_i32_e32 v245, 31, v66
	v_bfi_b32 v66, v245, v66, v244
	v_max_u32_e32 v244, v150, v66
	v_min_u32_e32 v150, v150, v66
	v_min_u32_e32 v151, v151, v244
	v_xor_b32_e32 v246, 0x7fffffff, v67
	v_ashrrev_i32_e32 v247, 31, v67
	v_bfi_b32 v67, v247, v67, v246
	v_max_u32_e32 v246, v249, v67
	v_min_u32_e32 v249, v249, v67
	v_min_u32_e32 v137, v137, v246
	v_xor_b32_e32 v240, 0x7fffffff, v68
	v_ashrrev_i32_e32 v241, 31, v68
	v_bfi_b32 v68, v241, v68, v240
	v_max_u32_e32 v240, v150, v68
	v_min_u32_e32 v150, v150, v68
	v_min_u32_e32 v151, v151, v240
	v_xor_b32_e32 v242, 0x7fffffff, v69
	v_ashrrev_i32_e32 v243, 31, v69
	v_bfi_b32 v69, v243, v69, v242
	v_max_u32_e32 v242, v249, v69
	v_min_u32_e32 v249, v249, v69
	v_min_u32_e32 v137, v137, v242
	v_xor_b32_e32 v244, 0x7fffffff, v70
	v_ashrrev_i32_e32 v245, 31, v70
	v_bfi_b32 v70, v245, v70, v244
	v_max_u32_e32 v244, v150, v70
	v_min_u32_e32 v150, v150, v70
	v_min_u32_e32 v151, v151, v244
	v_xor_b32_e32 v246, 0x7fffffff, v71
	v_ashrrev_i32_e32 v247, 31, v71
	v_bfi_b32 v71, v247, v71, v246
	v_max_u32_e32 v246, v249, v71
	v_min_u32_e32 v249, v249, v71
	v_min_u32_e32 v137, v137, v246
	v_xor_b32_e32 v240, 0x7fffffff, v72
	v_ashrrev_i32_e32 v241, 31, v72
	v_bfi_b32 v72, v241, v72, v240
	v_max_u32_e32 v240, v150, v72
	v_min_u32_e32 v150, v150, v72
	v_min_u32_e32 v151, v151, v240
	v_xor_b32_e32 v242, 0x7fffffff, v73
	v_ashrrev_i32_e32 v243, 31, v73
	v_bfi_b32 v73, v243, v73, v242
	v_max_u32_e32 v242, v249, v73
	v_min_u32_e32 v249, v249, v73
	v_min_u32_e32 v137, v137, v242
	v_xor_b32_e32 v244, 0x7fffffff, v74
	v_ashrrev_i32_e32 v245, 31, v74
	v_bfi_b32 v74, v245, v74, v244
	v_max_u32_e32 v244, v150, v74
	v_min_u32_e32 v150, v150, v74
	v_min_u32_e32 v151, v151, v244
	v_xor_b32_e32 v246, 0x7fffffff, v75
	v_ashrrev_i32_e32 v247, 31, v75
	v_bfi_b32 v75, v247, v75, v246
	v_max_u32_e32 v246, v249, v75
	v_min_u32_e32 v249, v249, v75
	v_min_u32_e32 v137, v137, v246
	v_xor_b32_e32 v240, 0x7fffffff, v76
	v_ashrrev_i32_e32 v241, 31, v76
	v_bfi_b32 v76, v241, v76, v240
	v_max_u32_e32 v240, v150, v76
	v_min_u32_e32 v150, v150, v76
	v_min_u32_e32 v151, v151, v240
	v_xor_b32_e32 v242, 0x7fffffff, v77
	v_ashrrev_i32_e32 v243, 31, v77
	v_bfi_b32 v77, v243, v77, v242
	v_max_u32_e32 v242, v249, v77
	v_min_u32_e32 v249, v249, v77
	v_min_u32_e32 v137, v137, v242
	v_xor_b32_e32 v244, 0x7fffffff, v78
	v_ashrrev_i32_e32 v245, 31, v78
	v_bfi_b32 v78, v245, v78, v244
	v_max_u32_e32 v244, v150, v78
	v_min_u32_e32 v150, v150, v78
	v_min_u32_e32 v151, v151, v244
	v_xor_b32_e32 v246, 0x7fffffff, v79
	v_ashrrev_i32_e32 v247, 31, v79
	v_bfi_b32 v79, v247, v79, v246
	v_max_u32_e32 v246, v249, v79
	v_min_u32_e32 v249, v249, v79
	v_min_u32_e32 v137, v137, v246
	s_branch .Lsel_cv_next4
.Lsel_cv_slow4:
	v_cmp_lt_i32_e32 vcc, 0x1000, v138
	v_xor_b32_e32 v240, 0x7fffffff, v64
	v_ashrrev_i32_e32 v241, 31, v64
	v_bfi_b32 v64, v241, v64, v240
	v_cndmask_b32_e32 v64, -1, v64, vcc
	v_max_u32_e32 v240, v150, v64
	v_min_u32_e32 v150, v150, v64
	v_min_u32_e32 v151, v151, v240
	v_cmp_lt_i32_e32 vcc, 0x1040, v138
	v_xor_b32_e32 v242, 0x7fffffff, v65
	v_ashrrev_i32_e32 v243, 31, v65
	v_bfi_b32 v65, v243, v65, v242
	v_cndmask_b32_e32 v65, -1, v65, vcc
	v_max_u32_e32 v242, v249, v65
	v_min_u32_e32 v249, v249, v65
	v_min_u32_e32 v137, v137, v242
	v_cmp_lt_i32_e32 vcc, 0x1080, v138
	v_xor_b32_e32 v244, 0x7fffffff, v66
	v_ashrrev_i32_e32 v245, 31, v66
	v_bfi_b32 v66, v245, v66, v244
	v_cndmask_b32_e32 v66, -1, v66, vcc
	v_max_u32_e32 v244, v150, v66
	v_min_u32_e32 v150, v150, v66
	v_min_u32_e32 v151, v151, v244
	v_cmp_lt_i32_e32 vcc, 0x10c0, v138
	v_xor_b32_e32 v246, 0x7fffffff, v67
	v_ashrrev_i32_e32 v247, 31, v67
	v_bfi_b32 v67, v247, v67, v246
	v_cndmask_b32_e32 v67, -1, v67, vcc
	v_max_u32_e32 v246, v249, v67
	v_min_u32_e32 v249, v249, v67
	v_min_u32_e32 v137, v137, v246
	v_cmp_lt_i32_e32 vcc, 0x1100, v138
	v_xor_b32_e32 v240, 0x7fffffff, v68
	v_ashrrev_i32_e32 v241, 31, v68
	v_bfi_b32 v68, v241, v68, v240
	v_cndmask_b32_e32 v68, -1, v68, vcc
	v_max_u32_e32 v240, v150, v68
	v_min_u32_e32 v150, v150, v68
	v_min_u32_e32 v151, v151, v240
	v_cmp_lt_i32_e32 vcc, 0x1140, v138
	v_xor_b32_e32 v242, 0x7fffffff, v69
	v_ashrrev_i32_e32 v243, 31, v69
	v_bfi_b32 v69, v243, v69, v242
	v_cndmask_b32_e32 v69, -1, v69, vcc
	v_max_u32_e32 v242, v249, v69
	v_min_u32_e32 v249, v249, v69
	v_min_u32_e32 v137, v137, v242
	v_cmp_lt_i32_e32 vcc, 0x1180, v138
	v_xor_b32_e32 v244, 0x7fffffff, v70
	v_ashrrev_i32_e32 v245, 31, v70
	v_bfi_b32 v70, v245, v70, v244
	v_cndmask_b32_e32 v70, -1, v70, vcc
	v_max_u32_e32 v244, v150, v70
	v_min_u32_e32 v150, v150, v70
	v_min_u32_e32 v151, v151, v244
	v_cmp_lt_i32_e32 vcc, 0x11c0, v138
	v_xor_b32_e32 v246, 0x7fffffff, v71
	v_ashrrev_i32_e32 v247, 31, v71
	v_bfi_b32 v71, v247, v71, v246
	v_cndmask_b32_e32 v71, -1, v71, vcc
	v_max_u32_e32 v246, v249, v71
	v_min_u32_e32 v249, v249, v71
	v_min_u32_e32 v137, v137, v246
	v_cmp_lt_i32_e32 vcc, 0x1200, v138
	v_xor_b32_e32 v240, 0x7fffffff, v72
	v_ashrrev_i32_e32 v241, 31, v72
	v_bfi_b32 v72, v241, v72, v240
	v_cndmask_b32_e32 v72, -1, v72, vcc
	v_max_u32_e32 v240, v150, v72
	v_min_u32_e32 v150, v150, v72
	v_min_u32_e32 v151, v151, v240
	v_cmp_lt_i32_e32 vcc, 0x1240, v138
	v_xor_b32_e32 v242, 0x7fffffff, v73
	v_ashrrev_i32_e32 v243, 31, v73
	v_bfi_b32 v73, v243, v73, v242
	v_cndmask_b32_e32 v73, -1, v73, vcc
	v_max_u32_e32 v242, v249, v73
	v_min_u32_e32 v249, v249, v73
	v_min_u32_e32 v137, v137, v242
	v_cmp_lt_i32_e32 vcc, 0x1280, v138
	v_xor_b32_e32 v244, 0x7fffffff, v74
	v_ashrrev_i32_e32 v245, 31, v74
	v_bfi_b32 v74, v245, v74, v244
	v_cndmask_b32_e32 v74, -1, v74, vcc
	v_max_u32_e32 v244, v150, v74
	v_min_u32_e32 v150, v150, v74
	v_min_u32_e32 v151, v151, v244
	v_cmp_lt_i32_e32 vcc, 0x12c0, v138
	v_xor_b32_e32 v246, 0x7fffffff, v75
	v_ashrrev_i32_e32 v247, 31, v75
	v_bfi_b32 v75, v247, v75, v246
	v_cndmask_b32_e32 v75, -1, v75, vcc
	v_max_u32_e32 v246, v249, v75
	v_min_u32_e32 v249, v249, v75
	v_min_u32_e32 v137, v137, v246
	v_cmp_lt_i32_e32 vcc, 0x1300, v138
	v_xor_b32_e32 v240, 0x7fffffff, v76
	v_ashrrev_i32_e32 v241, 31, v76
	v_bfi_b32 v76, v241, v76, v240
	v_cndmask_b32_e32 v76, -1, v76, vcc
	v_max_u32_e32 v240, v150, v76
	v_min_u32_e32 v150, v150, v76
	v_min_u32_e32 v151, v151, v240
	v_cmp_lt_i32_e32 vcc, 0x1340, v138
	v_xor_b32_e32 v242, 0x7fffffff, v77
	v_ashrrev_i32_e32 v243, 31, v77
	v_bfi_b32 v77, v243, v77, v242
	v_cndmask_b32_e32 v77, -1, v77, vcc
	v_max_u32_e32 v242, v249, v77
	v_min_u32_e32 v249, v249, v77
	v_min_u32_e32 v137, v137, v242
	v_cmp_lt_i32_e32 vcc, 0x1380, v138
	v_xor_b32_e32 v244, 0x7fffffff, v78
	v_ashrrev_i32_e32 v245, 31, v78
	v_bfi_b32 v78, v245, v78, v244
	v_cndmask_b32_e32 v78, -1, v78, vcc
	v_max_u32_e32 v244, v150, v78
	v_min_u32_e32 v150, v150, v78
	v_min_u32_e32 v151, v151, v244
	v_cmp_lt_i32_e32 vcc, 0x13c0, v138
	v_xor_b32_e32 v246, 0x7fffffff, v79
	v_ashrrev_i32_e32 v247, 31, v79
	v_bfi_b32 v79, v247, v79, v246
	v_cndmask_b32_e32 v79, -1, v79, vcc
	v_max_u32_e32 v246, v249, v79
	v_min_u32_e32 v249, v249, v79
	v_min_u32_e32 v137, v137, v246
.Lsel_cv_next4:
	s_cmpk_le_u32 s34, 80
	s_cbranch_scc1 .Lsel_cv_done
	s_cmpk_ge_u32 s33, 6144
	s_cbranch_scc0 .Lsel_cv_slow5
	v_xor_b32_e32 v240, 0x7fffffff, v80
	v_ashrrev_i32_e32 v241, 31, v80
	v_bfi_b32 v80, v241, v80, v240
	v_max_u32_e32 v240, v150, v80
	v_min_u32_e32 v150, v150, v80
	v_min_u32_e32 v151, v151, v240
	v_xor_b32_e32 v242, 0x7fffffff, v81
	v_ashrrev_i32_e32 v243, 31, v81
	v_bfi_b32 v81, v243, v81, v242
	v_max_u32_e32 v242, v249, v81
	v_min_u32_e32 v249, v249, v81
	v_min_u32_e32 v137, v137, v242
	v_xor_b32_e32 v244, 0x7fffffff, v82
	v_ashrrev_i32_e32 v245, 31, v82
	v_bfi_b32 v82, v245, v82, v244
	v_max_u32_e32 v244, v150, v82
	v_min_u32_e32 v150, v150, v82
	v_min_u32_e32 v151, v151, v244
	v_xor_b32_e32 v246, 0x7fffffff, v83
	v_ashrrev_i32_e32 v247, 31, v83
	v_bfi_b32 v83, v247, v83, v246
	v_max_u32_e32 v246, v249, v83
	v_min_u32_e32 v249, v249, v83
	v_min_u32_e32 v137, v137, v246
	v_xor_b32_e32 v240, 0x7fffffff, v84
	v_ashrrev_i32_e32 v241, 31, v84
	v_bfi_b32 v84, v241, v84, v240
	v_max_u32_e32 v240, v150, v84
	v_min_u32_e32 v150, v150, v84
	v_min_u32_e32 v151, v151, v240
	v_xor_b32_e32 v242, 0x7fffffff, v85
	v_ashrrev_i32_e32 v243, 31, v85
	v_bfi_b32 v85, v243, v85, v242
	v_max_u32_e32 v242, v249, v85
	v_min_u32_e32 v249, v249, v85
	v_min_u32_e32 v137, v137, v242
	v_xor_b32_e32 v244, 0x7fffffff, v86
	v_ashrrev_i32_e32 v245, 31, v86
	v_bfi_b32 v86, v245, v86, v244
	v_max_u32_e32 v244, v150, v86
	v_min_u32_e32 v150, v150, v86
	v_min_u32_e32 v151, v151, v244
	v_xor_b32_e32 v246, 0x7fffffff, v87
	v_ashrrev_i32_e32 v247, 31, v87
	v_bfi_b32 v87, v247, v87, v246
	v_max_u32_e32 v246, v249, v87
	v_min_u32_e32 v249, v249, v87
	v_min_u32_e32 v137, v137, v246
	v_xor_b32_e32 v240, 0x7fffffff, v88
	v_ashrrev_i32_e32 v241, 31, v88
	v_bfi_b32 v88, v241, v88, v240
	v_max_u32_e32 v240, v150, v88
	v_min_u32_e32 v150, v150, v88
	v_min_u32_e32 v151, v151, v240
	v_xor_b32_e32 v242, 0x7fffffff, v89
	v_ashrrev_i32_e32 v243, 31, v89
	v_bfi_b32 v89, v243, v89, v242
	v_max_u32_e32 v242, v249, v89
	v_min_u32_e32 v249, v249, v89
	v_min_u32_e32 v137, v137, v242
	v_xor_b32_e32 v244, 0x7fffffff, v90
	v_ashrrev_i32_e32 v245, 31, v90
	v_bfi_b32 v90, v245, v90, v244
	v_max_u32_e32 v244, v150, v90
	v_min_u32_e32 v150, v150, v90
	v_min_u32_e32 v151, v151, v244
	v_xor_b32_e32 v246, 0x7fffffff, v91
	v_ashrrev_i32_e32 v247, 31, v91
	v_bfi_b32 v91, v247, v91, v246
	v_max_u32_e32 v246, v249, v91
	v_min_u32_e32 v249, v249, v91
	v_min_u32_e32 v137, v137, v246
	v_xor_b32_e32 v240, 0x7fffffff, v92
	v_ashrrev_i32_e32 v241, 31, v92
	v_bfi_b32 v92, v241, v92, v240
	v_max_u32_e32 v240, v150, v92
	v_min_u32_e32 v150, v150, v92
	v_min_u32_e32 v151, v151, v240
	v_xor_b32_e32 v242, 0x7fffffff, v93
	v_ashrrev_i32_e32 v243, 31, v93
	v_bfi_b32 v93, v243, v93, v242
	v_max_u32_e32 v242, v249, v93
	v_min_u32_e32 v249, v249, v93
	v_min_u32_e32 v137, v137, v242
	v_xor_b32_e32 v244, 0x7fffffff, v94
	v_ashrrev_i32_e32 v245, 31, v94
	v_bfi_b32 v94, v245, v94, v244
	v_max_u32_e32 v244, v150, v94
	v_min_u32_e32 v150, v150, v94
	v_min_u32_e32 v151, v151, v244
	v_xor_b32_e32 v246, 0x7fffffff, v95
	v_ashrrev_i32_e32 v247, 31, v95
	v_bfi_b32 v95, v247, v95, v246
	v_max_u32_e32 v246, v249, v95
	v_min_u32_e32 v249, v249, v95
	v_min_u32_e32 v137, v137, v246
	s_branch .Lsel_cv_next5
.Lsel_cv_slow5:
	v_cmp_lt_i32_e32 vcc, 0x1400, v138
	v_xor_b32_e32 v240, 0x7fffffff, v80
	v_ashrrev_i32_e32 v241, 31, v80
	v_bfi_b32 v80, v241, v80, v240
	v_cndmask_b32_e32 v80, -1, v80, vcc
	v_max_u32_e32 v240, v150, v80
	v_min_u32_e32 v150, v150, v80
	v_min_u32_e32 v151, v151, v240
	v_cmp_lt_i32_e32 vcc, 0x1440, v138
	v_xor_b32_e32 v242, 0x7fffffff, v81
	v_ashrrev_i32_e32 v243, 31, v81
	v_bfi_b32 v81, v243, v81, v242
	v_cndmask_b32_e32 v81, -1, v81, vcc
	v_max_u32_e32 v242, v249, v81
	v_min_u32_e32 v249, v249, v81
	v_min_u32_e32 v137, v137, v242
	v_cmp_lt_i32_e32 vcc, 0x1480, v138
	v_xor_b32_e32 v244, 0x7fffffff, v82
	v_ashrrev_i32_e32 v245, 31, v82
	v_bfi_b32 v82, v245, v82, v244
	v_cndmask_b32_e32 v82, -1, v82, vcc
	v_max_u32_e32 v244, v150, v82
	v_min_u32_e32 v150, v150, v82
	v_min_u32_e32 v151, v151, v244
	v_cmp_lt_i32_e32 vcc, 0x14c0, v138
	v_xor_b32_e32 v246, 0x7fffffff, v83
	v_ashrrev_i32_e32 v247, 31, v83
	v_bfi_b32 v83, v247, v83, v246
	v_cndmask_b32_e32 v83, -1, v83, vcc
	v_max_u32_e32 v246, v249, v83
	v_min_u32_e32 v249, v249, v83
	v_min_u32_e32 v137, v137, v246
	v_cmp_lt_i32_e32 vcc, 0x1500, v138
	v_xor_b32_e32 v240, 0x7fffffff, v84
	v_ashrrev_i32_e32 v241, 31, v84
	v_bfi_b32 v84, v241, v84, v240
	v_cndmask_b32_e32 v84, -1, v84, vcc
	v_max_u32_e32 v240, v150, v84
	v_min_u32_e32 v150, v150, v84
	v_min_u32_e32 v151, v151, v240
	v_cmp_lt_i32_e32 vcc, 0x1540, v138
	v_xor_b32_e32 v242, 0x7fffffff, v85
	v_ashrrev_i32_e32 v243, 31, v85
	v_bfi_b32 v85, v243, v85, v242
	v_cndmask_b32_e32 v85, -1, v85, vcc
	v_max_u32_e32 v242, v249, v85
	v_min_u32_e32 v249, v249, v85
	v_min_u32_e32 v137, v137, v242
	v_cmp_lt_i32_e32 vcc, 0x1580, v138
	v_xor_b32_e32 v244, 0x7fffffff, v86
	v_ashrrev_i32_e32 v245, 31, v86
	v_bfi_b32 v86, v245, v86, v244
	v_cndmask_b32_e32 v86, -1, v86, vcc
	v_max_u32_e32 v244, v150, v86
	v_min_u32_e32 v150, v150, v86
	v_min_u32_e32 v151, v151, v244
	v_cmp_lt_i32_e32 vcc, 0x15c0, v138
	v_xor_b32_e32 v246, 0x7fffffff, v87
	v_ashrrev_i32_e32 v247, 31, v87
	v_bfi_b32 v87, v247, v87, v246
	v_cndmask_b32_e32 v87, -1, v87, vcc
	v_max_u32_e32 v246, v249, v87
	v_min_u32_e32 v249, v249, v87
	v_min_u32_e32 v137, v137, v246
	v_cmp_lt_i32_e32 vcc, 0x1600, v138
	v_xor_b32_e32 v240, 0x7fffffff, v88
	v_ashrrev_i32_e32 v241, 31, v88
	v_bfi_b32 v88, v241, v88, v240
	v_cndmask_b32_e32 v88, -1, v88, vcc
	v_max_u32_e32 v240, v150, v88
	v_min_u32_e32 v150, v150, v88
	v_min_u32_e32 v151, v151, v240
	v_cmp_lt_i32_e32 vcc, 0x1640, v138
	v_xor_b32_e32 v242, 0x7fffffff, v89
	v_ashrrev_i32_e32 v243, 31, v89
	v_bfi_b32 v89, v243, v89, v242
	v_cndmask_b32_e32 v89, -1, v89, vcc
	v_max_u32_e32 v242, v249, v89
	v_min_u32_e32 v249, v249, v89
	v_min_u32_e32 v137, v137, v242
	v_cmp_lt_i32_e32 vcc, 0x1680, v138
	v_xor_b32_e32 v244, 0x7fffffff, v90
	v_ashrrev_i32_e32 v245, 31, v90
	v_bfi_b32 v90, v245, v90, v244
	v_cndmask_b32_e32 v90, -1, v90, vcc
	v_max_u32_e32 v244, v150, v90
	v_min_u32_e32 v150, v150, v90
	v_min_u32_e32 v151, v151, v244
	v_cmp_lt_i32_e32 vcc, 0x16c0, v138
	v_xor_b32_e32 v246, 0x7fffffff, v91
	v_ashrrev_i32_e32 v247, 31, v91
	v_bfi_b32 v91, v247, v91, v246
	v_cndmask_b32_e32 v91, -1, v91, vcc
	v_max_u32_e32 v246, v249, v91
	v_min_u32_e32 v249, v249, v91
	v_min_u32_e32 v137, v137, v246
	v_cmp_lt_i32_e32 vcc, 0x1700, v138
	v_xor_b32_e32 v240, 0x7fffffff, v92
	v_ashrrev_i32_e32 v241, 31, v92
	v_bfi_b32 v92, v241, v92, v240
	v_cndmask_b32_e32 v92, -1, v92, vcc
	v_max_u32_e32 v240, v150, v92
	v_min_u32_e32 v150, v150, v92
	v_min_u32_e32 v151, v151, v240
	v_cmp_lt_i32_e32 vcc, 0x1740, v138
	v_xor_b32_e32 v242, 0x7fffffff, v93
	v_ashrrev_i32_e32 v243, 31, v93
	v_bfi_b32 v93, v243, v93, v242
	v_cndmask_b32_e32 v93, -1, v93, vcc
	v_max_u32_e32 v242, v249, v93
	v_min_u32_e32 v249, v249, v93
	v_min_u32_e32 v137, v137, v242
	v_cmp_lt_i32_e32 vcc, 0x1780, v138
	v_xor_b32_e32 v244, 0x7fffffff, v94
	v_ashrrev_i32_e32 v245, 31, v94
	v_bfi_b32 v94, v245, v94, v244
	v_cndmask_b32_e32 v94, -1, v94, vcc
	v_max_u32_e32 v244, v150, v94
	v_min_u32_e32 v150, v150, v94
	v_min_u32_e32 v151, v151, v244
	v_cmp_lt_i32_e32 vcc, 0x17c0, v138
	v_xor_b32_e32 v246, 0x7fffffff, v95
	v_ashrrev_i32_e32 v247, 31, v95
	v_bfi_b32 v95, v247, v95, v246
	v_cndmask_b32_e32 v95, -1, v95, vcc
	v_max_u32_e32 v246, v249, v95
	v_min_u32_e32 v249, v249, v95
	v_min_u32_e32 v137, v137, v246
.Lsel_cv_next5:
	s_cmpk_le_u32 s34, 96
	s_cbranch_scc1 .Lsel_cv_done
	s_cmpk_ge_u32 s33, 7168
	s_cbranch_scc0 .Lsel_cv_slow6
	v_xor_b32_e32 v240, 0x7fffffff, v208
	v_ashrrev_i32_e32 v241, 31, v208
	v_bfi_b32 v208, v241, v208, v240
	v_max_u32_e32 v240, v150, v208
	v_min_u32_e32 v150, v150, v208
	v_min_u32_e32 v151, v151, v240
	v_xor_b32_e32 v242, 0x7fffffff, v209
	v_ashrrev_i32_e32 v243, 31, v209
	v_bfi_b32 v209, v243, v209, v242
	v_max_u32_e32 v242, v249, v209
	v_min_u32_e32 v249, v249, v209
	v_min_u32_e32 v137, v137, v242
	v_xor_b32_e32 v244, 0x7fffffff, v210
	v_ashrrev_i32_e32 v245, 31, v210
	v_bfi_b32 v210, v245, v210, v244
	v_max_u32_e32 v244, v150, v210
	v_min_u32_e32 v150, v150, v210
	v_min_u32_e32 v151, v151, v244
	v_xor_b32_e32 v246, 0x7fffffff, v211
	v_ashrrev_i32_e32 v247, 31, v211
	v_bfi_b32 v211, v247, v211, v246
	v_max_u32_e32 v246, v249, v211
	v_min_u32_e32 v249, v249, v211
	v_min_u32_e32 v137, v137, v246
	v_xor_b32_e32 v240, 0x7fffffff, v212
	v_ashrrev_i32_e32 v241, 31, v212
	v_bfi_b32 v212, v241, v212, v240
	v_max_u32_e32 v240, v150, v212
	v_min_u32_e32 v150, v150, v212
	v_min_u32_e32 v151, v151, v240
	v_xor_b32_e32 v242, 0x7fffffff, v213
	v_ashrrev_i32_e32 v243, 31, v213
	v_bfi_b32 v213, v243, v213, v242
	v_max_u32_e32 v242, v249, v213
	v_min_u32_e32 v249, v249, v213
	v_min_u32_e32 v137, v137, v242
	v_xor_b32_e32 v244, 0x7fffffff, v214
	v_ashrrev_i32_e32 v245, 31, v214
	v_bfi_b32 v214, v245, v214, v244
	v_max_u32_e32 v244, v150, v214
	v_min_u32_e32 v150, v150, v214
	v_min_u32_e32 v151, v151, v244
	v_xor_b32_e32 v246, 0x7fffffff, v215
	v_ashrrev_i32_e32 v247, 31, v215
	v_bfi_b32 v215, v247, v215, v246
	v_max_u32_e32 v246, v249, v215
	v_min_u32_e32 v249, v249, v215
	v_min_u32_e32 v137, v137, v246
	v_xor_b32_e32 v240, 0x7fffffff, v216
	v_ashrrev_i32_e32 v241, 31, v216
	v_bfi_b32 v216, v241, v216, v240
	v_max_u32_e32 v240, v150, v216
	v_min_u32_e32 v150, v150, v216
	v_min_u32_e32 v151, v151, v240
	v_xor_b32_e32 v242, 0x7fffffff, v217
	v_ashrrev_i32_e32 v243, 31, v217
	v_bfi_b32 v217, v243, v217, v242
	v_max_u32_e32 v242, v249, v217
	v_min_u32_e32 v249, v249, v217
	v_min_u32_e32 v137, v137, v242
	v_xor_b32_e32 v244, 0x7fffffff, v218
	v_ashrrev_i32_e32 v245, 31, v218
	v_bfi_b32 v218, v245, v218, v244
	v_max_u32_e32 v244, v150, v218
	v_min_u32_e32 v150, v150, v218
	v_min_u32_e32 v151, v151, v244
	v_xor_b32_e32 v246, 0x7fffffff, v219
	v_ashrrev_i32_e32 v247, 31, v219
	v_bfi_b32 v219, v247, v219, v246
	v_max_u32_e32 v246, v249, v219
	v_min_u32_e32 v249, v249, v219
	v_min_u32_e32 v137, v137, v246
	v_xor_b32_e32 v240, 0x7fffffff, v220
	v_ashrrev_i32_e32 v241, 31, v220
	v_bfi_b32 v220, v241, v220, v240
	v_max_u32_e32 v240, v150, v220
	v_min_u32_e32 v150, v150, v220
	v_min_u32_e32 v151, v151, v240
	v_xor_b32_e32 v242, 0x7fffffff, v221
	v_ashrrev_i32_e32 v243, 31, v221
	v_bfi_b32 v221, v243, v221, v242
	v_max_u32_e32 v242, v249, v221
	v_min_u32_e32 v249, v249, v221
	v_min_u32_e32 v137, v137, v242
	v_xor_b32_e32 v244, 0x7fffffff, v222
	v_ashrrev_i32_e32 v245, 31, v222
	v_bfi_b32 v222, v245, v222, v244
	v_max_u32_e32 v244, v150, v222
	v_min_u32_e32 v150, v150, v222
	v_min_u32_e32 v151, v151, v244
	v_xor_b32_e32 v246, 0x7fffffff, v223
	v_ashrrev_i32_e32 v247, 31, v223
	v_bfi_b32 v223, v247, v223, v246
	v_max_u32_e32 v246, v249, v223
	v_min_u32_e32 v249, v249, v223
	v_min_u32_e32 v137, v137, v246
	s_branch .Lsel_cv_next6
.Lsel_cv_slow6:
	v_cmp_lt_i32_e32 vcc, 0x1800, v138
	v_xor_b32_e32 v240, 0x7fffffff, v208
	v_ashrrev_i32_e32 v241, 31, v208
	v_bfi_b32 v208, v241, v208, v240
	v_cndmask_b32_e32 v208, -1, v208, vcc
	v_max_u32_e32 v240, v150, v208
	v_min_u32_e32 v150, v150, v208
	v_min_u32_e32 v151, v151, v240
	v_cmp_lt_i32_e32 vcc, 0x1840, v138
	v_xor_b32_e32 v242, 0x7fffffff, v209
	v_ashrrev_i32_e32 v243, 31, v209
	v_bfi_b32 v209, v243, v209, v242
	v_cndmask_b32_e32 v209, -1, v209, vcc
	v_max_u32_e32 v242, v249, v209
	v_min_u32_e32 v249, v249, v209
	v_min_u32_e32 v137, v137, v242
	v_cmp_lt_i32_e32 vcc, 0x1880, v138
	v_xor_b32_e32 v244, 0x7fffffff, v210
	v_ashrrev_i32_e32 v245, 31, v210
	v_bfi_b32 v210, v245, v210, v244
	v_cndmask_b32_e32 v210, -1, v210, vcc
	v_max_u32_e32 v244, v150, v210
	v_min_u32_e32 v150, v150, v210
	v_min_u32_e32 v151, v151, v244
	v_cmp_lt_i32_e32 vcc, 0x18c0, v138
	v_xor_b32_e32 v246, 0x7fffffff, v211
	v_ashrrev_i32_e32 v247, 31, v211
	v_bfi_b32 v211, v247, v211, v246
	v_cndmask_b32_e32 v211, -1, v211, vcc
	v_max_u32_e32 v246, v249, v211
	v_min_u32_e32 v249, v249, v211
	v_min_u32_e32 v137, v137, v246
	v_cmp_lt_i32_e32 vcc, 0x1900, v138
	v_xor_b32_e32 v240, 0x7fffffff, v212
	v_ashrrev_i32_e32 v241, 31, v212
	v_bfi_b32 v212, v241, v212, v240
	v_cndmask_b32_e32 v212, -1, v212, vcc
	v_max_u32_e32 v240, v150, v212
	v_min_u32_e32 v150, v150, v212
	v_min_u32_e32 v151, v151, v240
	v_cmp_lt_i32_e32 vcc, 0x1940, v138
	v_xor_b32_e32 v242, 0x7fffffff, v213
	v_ashrrev_i32_e32 v243, 31, v213
	v_bfi_b32 v213, v243, v213, v242
	v_cndmask_b32_e32 v213, -1, v213, vcc
	v_max_u32_e32 v242, v249, v213
	v_min_u32_e32 v249, v249, v213
	v_min_u32_e32 v137, v137, v242
	v_cmp_lt_i32_e32 vcc, 0x1980, v138
	v_xor_b32_e32 v244, 0x7fffffff, v214
	v_ashrrev_i32_e32 v245, 31, v214
	v_bfi_b32 v214, v245, v214, v244
	v_cndmask_b32_e32 v214, -1, v214, vcc
	v_max_u32_e32 v244, v150, v214
	v_min_u32_e32 v150, v150, v214
	v_min_u32_e32 v151, v151, v244
	v_cmp_lt_i32_e32 vcc, 0x19c0, v138
	v_xor_b32_e32 v246, 0x7fffffff, v215
	v_ashrrev_i32_e32 v247, 31, v215
	v_bfi_b32 v215, v247, v215, v246
	v_cndmask_b32_e32 v215, -1, v215, vcc
	v_max_u32_e32 v246, v249, v215
	v_min_u32_e32 v249, v249, v215
	v_min_u32_e32 v137, v137, v246
	v_cmp_lt_i32_e32 vcc, 0x1a00, v138
	v_xor_b32_e32 v240, 0x7fffffff, v216
	v_ashrrev_i32_e32 v241, 31, v216
	v_bfi_b32 v216, v241, v216, v240
	v_cndmask_b32_e32 v216, -1, v216, vcc
	v_max_u32_e32 v240, v150, v216
	v_min_u32_e32 v150, v150, v216
	v_min_u32_e32 v151, v151, v240
	v_cmp_lt_i32_e32 vcc, 0x1a40, v138
	v_xor_b32_e32 v242, 0x7fffffff, v217
	v_ashrrev_i32_e32 v243, 31, v217
	v_bfi_b32 v217, v243, v217, v242
	v_cndmask_b32_e32 v217, -1, v217, vcc
	v_max_u32_e32 v242, v249, v217
	v_min_u32_e32 v249, v249, v217
	v_min_u32_e32 v137, v137, v242
	v_cmp_lt_i32_e32 vcc, 0x1a80, v138
	v_xor_b32_e32 v244, 0x7fffffff, v218
	v_ashrrev_i32_e32 v245, 31, v218
	v_bfi_b32 v218, v245, v218, v244
	v_cndmask_b32_e32 v218, -1, v218, vcc
	v_max_u32_e32 v244, v150, v218
	v_min_u32_e32 v150, v150, v218
	v_min_u32_e32 v151, v151, v244
	v_cmp_lt_i32_e32 vcc, 0x1ac0, v138
	v_xor_b32_e32 v246, 0x7fffffff, v219
	v_ashrrev_i32_e32 v247, 31, v219
	v_bfi_b32 v219, v247, v219, v246
	v_cndmask_b32_e32 v219, -1, v219, vcc
	v_max_u32_e32 v246, v249, v219
	v_min_u32_e32 v249, v249, v219
	v_min_u32_e32 v137, v137, v246
	v_cmp_lt_i32_e32 vcc, 0x1b00, v138
	v_xor_b32_e32 v240, 0x7fffffff, v220
	v_ashrrev_i32_e32 v241, 31, v220
	v_bfi_b32 v220, v241, v220, v240
	v_cndmask_b32_e32 v220, -1, v220, vcc
	v_max_u32_e32 v240, v150, v220
	v_min_u32_e32 v150, v150, v220
	v_min_u32_e32 v151, v151, v240
	v_cmp_lt_i32_e32 vcc, 0x1b40, v138
	v_xor_b32_e32 v242, 0x7fffffff, v221
	v_ashrrev_i32_e32 v243, 31, v221
	v_bfi_b32 v221, v243, v221, v242
	v_cndmask_b32_e32 v221, -1, v221, vcc
	v_max_u32_e32 v242, v249, v221
	v_min_u32_e32 v249, v249, v221
	v_min_u32_e32 v137, v137, v242
	v_cmp_lt_i32_e32 vcc, 0x1b80, v138
	v_xor_b32_e32 v244, 0x7fffffff, v222
	v_ashrrev_i32_e32 v245, 31, v222
	v_bfi_b32 v222, v245, v222, v244
	v_cndmask_b32_e32 v222, -1, v222, vcc
	v_max_u32_e32 v244, v150, v222
	v_min_u32_e32 v150, v150, v222
	v_min_u32_e32 v151, v151, v244
	v_cmp_lt_i32_e32 vcc, 0x1bc0, v138
	v_xor_b32_e32 v246, 0x7fffffff, v223
	v_ashrrev_i32_e32 v247, 31, v223
	v_bfi_b32 v223, v247, v223, v246
	v_cndmask_b32_e32 v223, -1, v223, vcc
	v_max_u32_e32 v246, v249, v223
	v_min_u32_e32 v249, v249, v223
	v_min_u32_e32 v137, v137, v246
.Lsel_cv_next6:
	s_cmpk_le_u32 s34, 112
	s_cbranch_scc1 .Lsel_cv_done
	s_cmpk_ge_u32 s33, 8192
	s_cbranch_scc0 .Lsel_cv_slow7
	v_xor_b32_e32 v240, 0x7fffffff, v224
	v_ashrrev_i32_e32 v241, 31, v224
	v_bfi_b32 v224, v241, v224, v240
	v_max_u32_e32 v240, v150, v224
	v_min_u32_e32 v150, v150, v224
	v_min_u32_e32 v151, v151, v240
	v_xor_b32_e32 v242, 0x7fffffff, v225
	v_ashrrev_i32_e32 v243, 31, v225
	v_bfi_b32 v225, v243, v225, v242
	v_max_u32_e32 v242, v249, v225
	v_min_u32_e32 v249, v249, v225
	v_min_u32_e32 v137, v137, v242
	v_xor_b32_e32 v244, 0x7fffffff, v226
	v_ashrrev_i32_e32 v245, 31, v226
	v_bfi_b32 v226, v245, v226, v244
	v_max_u32_e32 v244, v150, v226
	v_min_u32_e32 v150, v150, v226
	v_min_u32_e32 v151, v151, v244
	v_xor_b32_e32 v246, 0x7fffffff, v227
	v_ashrrev_i32_e32 v247, 31, v227
	v_bfi_b32 v227, v247, v227, v246
	v_max_u32_e32 v246, v249, v227
	v_min_u32_e32 v249, v249, v227
	v_min_u32_e32 v137, v137, v246
	v_xor_b32_e32 v240, 0x7fffffff, v228
	v_ashrrev_i32_e32 v241, 31, v228
	v_bfi_b32 v228, v241, v228, v240
	v_max_u32_e32 v240, v150, v228
	v_min_u32_e32 v150, v150, v228
	v_min_u32_e32 v151, v151, v240
	v_xor_b32_e32 v242, 0x7fffffff, v229
	v_ashrrev_i32_e32 v243, 31, v229
	v_bfi_b32 v229, v243, v229, v242
	v_max_u32_e32 v242, v249, v229
	v_min_u32_e32 v249, v249, v229
	v_min_u32_e32 v137, v137, v242
	v_xor_b32_e32 v244, 0x7fffffff, v230
	v_ashrrev_i32_e32 v245, 31, v230
	v_bfi_b32 v230, v245, v230, v244
	v_max_u32_e32 v244, v150, v230
	v_min_u32_e32 v150, v150, v230
	v_min_u32_e32 v151, v151, v244
	v_xor_b32_e32 v246, 0x7fffffff, v231
	v_ashrrev_i32_e32 v247, 31, v231
	v_bfi_b32 v231, v247, v231, v246
	v_max_u32_e32 v246, v249, v231
	v_min_u32_e32 v249, v249, v231
	v_min_u32_e32 v137, v137, v246
	v_xor_b32_e32 v240, 0x7fffffff, v232
	v_ashrrev_i32_e32 v241, 31, v232
	v_bfi_b32 v232, v241, v232, v240
	v_max_u32_e32 v240, v150, v232
	v_min_u32_e32 v150, v150, v232
	v_min_u32_e32 v151, v151, v240
	v_xor_b32_e32 v242, 0x7fffffff, v233
	v_ashrrev_i32_e32 v243, 31, v233
	v_bfi_b32 v233, v243, v233, v242
	v_max_u32_e32 v242, v249, v233
	v_min_u32_e32 v249, v249, v233
	v_min_u32_e32 v137, v137, v242
	v_xor_b32_e32 v244, 0x7fffffff, v234
	v_ashrrev_i32_e32 v245, 31, v234
	v_bfi_b32 v234, v245, v234, v244
	v_max_u32_e32 v244, v150, v234
	v_min_u32_e32 v150, v150, v234
	v_min_u32_e32 v151, v151, v244
	v_xor_b32_e32 v246, 0x7fffffff, v235
	v_ashrrev_i32_e32 v247, 31, v235
	v_bfi_b32 v235, v247, v235, v246
	v_max_u32_e32 v246, v249, v235
	v_min_u32_e32 v249, v249, v235
	v_min_u32_e32 v137, v137, v246
	v_xor_b32_e32 v240, 0x7fffffff, v236
	v_ashrrev_i32_e32 v241, 31, v236
	v_bfi_b32 v236, v241, v236, v240
	v_max_u32_e32 v240, v150, v236
	v_min_u32_e32 v150, v150, v236
	v_min_u32_e32 v151, v151, v240
	v_xor_b32_e32 v242, 0x7fffffff, v237
	v_ashrrev_i32_e32 v243, 31, v237
	v_bfi_b32 v237, v243, v237, v242
	v_max_u32_e32 v242, v249, v237
	v_min_u32_e32 v249, v249, v237
	v_min_u32_e32 v137, v137, v242
	v_xor_b32_e32 v244, 0x7fffffff, v238
	v_ashrrev_i32_e32 v245, 31, v238
	v_bfi_b32 v238, v245, v238, v244
	v_max_u32_e32 v244, v150, v238
	v_min_u32_e32 v150, v150, v238
	v_min_u32_e32 v151, v151, v244
	v_xor_b32_e32 v246, 0x7fffffff, v239
	v_ashrrev_i32_e32 v247, 31, v239
	v_bfi_b32 v239, v247, v239, v246
	v_max_u32_e32 v246, v249, v239
	v_min_u32_e32 v249, v249, v239
	v_min_u32_e32 v137, v137, v246
	s_branch .Lsel_cv_next7
.Lsel_cv_slow7:
	v_cmp_lt_i32_e32 vcc, 0x1c00, v138
	v_xor_b32_e32 v240, 0x7fffffff, v224
	v_ashrrev_i32_e32 v241, 31, v224
	v_bfi_b32 v224, v241, v224, v240
	v_cndmask_b32_e32 v224, -1, v224, vcc
	v_max_u32_e32 v240, v150, v224
	v_min_u32_e32 v150, v150, v224
	v_min_u32_e32 v151, v151, v240
	v_cmp_lt_i32_e32 vcc, 0x1c40, v138
	v_xor_b32_e32 v242, 0x7fffffff, v225
	v_ashrrev_i32_e32 v243, 31, v225
	v_bfi_b32 v225, v243, v225, v242
	v_cndmask_b32_e32 v225, -1, v225, vcc
	v_max_u32_e32 v242, v249, v225
	v_min_u32_e32 v249, v249, v225
	v_min_u32_e32 v137, v137, v242
	v_cmp_lt_i32_e32 vcc, 0x1c80, v138
	v_xor_b32_e32 v244, 0x7fffffff, v226
	v_ashrrev_i32_e32 v245, 31, v226
	v_bfi_b32 v226, v245, v226, v244
	v_cndmask_b32_e32 v226, -1, v226, vcc
	v_max_u32_e32 v244, v150, v226
	v_min_u32_e32 v150, v150, v226
	v_min_u32_e32 v151, v151, v244
	v_cmp_lt_i32_e32 vcc, 0x1cc0, v138
	v_xor_b32_e32 v246, 0x7fffffff, v227
	v_ashrrev_i32_e32 v247, 31, v227
	v_bfi_b32 v227, v247, v227, v246
	v_cndmask_b32_e32 v227, -1, v227, vcc
	v_max_u32_e32 v246, v249, v227
	v_min_u32_e32 v249, v249, v227
	v_min_u32_e32 v137, v137, v246
	v_cmp_lt_i32_e32 vcc, 0x1d00, v138
	v_xor_b32_e32 v240, 0x7fffffff, v228
	v_ashrrev_i32_e32 v241, 31, v228
	v_bfi_b32 v228, v241, v228, v240
	v_cndmask_b32_e32 v228, -1, v228, vcc
	v_max_u32_e32 v240, v150, v228
	v_min_u32_e32 v150, v150, v228
	v_min_u32_e32 v151, v151, v240
	v_cmp_lt_i32_e32 vcc, 0x1d40, v138
	v_xor_b32_e32 v242, 0x7fffffff, v229
	v_ashrrev_i32_e32 v243, 31, v229
	v_bfi_b32 v229, v243, v229, v242
	v_cndmask_b32_e32 v229, -1, v229, vcc
	v_max_u32_e32 v242, v249, v229
	v_min_u32_e32 v249, v249, v229
	v_min_u32_e32 v137, v137, v242
	v_cmp_lt_i32_e32 vcc, 0x1d80, v138
	v_xor_b32_e32 v244, 0x7fffffff, v230
	v_ashrrev_i32_e32 v245, 31, v230
	v_bfi_b32 v230, v245, v230, v244
	v_cndmask_b32_e32 v230, -1, v230, vcc
	v_max_u32_e32 v244, v150, v230
	v_min_u32_e32 v150, v150, v230
	v_min_u32_e32 v151, v151, v244
	v_cmp_lt_i32_e32 vcc, 0x1dc0, v138
	v_xor_b32_e32 v246, 0x7fffffff, v231
	v_ashrrev_i32_e32 v247, 31, v231
	v_bfi_b32 v231, v247, v231, v246
	v_cndmask_b32_e32 v231, -1, v231, vcc
	v_max_u32_e32 v246, v249, v231
	v_min_u32_e32 v249, v249, v231
	v_min_u32_e32 v137, v137, v246
	v_cmp_lt_i32_e32 vcc, 0x1e00, v138
	v_xor_b32_e32 v240, 0x7fffffff, v232
	v_ashrrev_i32_e32 v241, 31, v232
	v_bfi_b32 v232, v241, v232, v240
	v_cndmask_b32_e32 v232, -1, v232, vcc
	v_max_u32_e32 v240, v150, v232
	v_min_u32_e32 v150, v150, v232
	v_min_u32_e32 v151, v151, v240
	v_cmp_lt_i32_e32 vcc, 0x1e40, v138
	v_xor_b32_e32 v242, 0x7fffffff, v233
	v_ashrrev_i32_e32 v243, 31, v233
	v_bfi_b32 v233, v243, v233, v242
	v_cndmask_b32_e32 v233, -1, v233, vcc
	v_max_u32_e32 v242, v249, v233
	v_min_u32_e32 v249, v249, v233
	v_min_u32_e32 v137, v137, v242
	v_cmp_lt_i32_e32 vcc, 0x1e80, v138
	v_xor_b32_e32 v244, 0x7fffffff, v234
	v_ashrrev_i32_e32 v245, 31, v234
	v_bfi_b32 v234, v245, v234, v244
	v_cndmask_b32_e32 v234, -1, v234, vcc
	v_max_u32_e32 v244, v150, v234
	v_min_u32_e32 v150, v150, v234
	v_min_u32_e32 v151, v151, v244
	v_cmp_lt_i32_e32 vcc, 0x1ec0, v138
	v_xor_b32_e32 v246, 0x7fffffff, v235
	v_ashrrev_i32_e32 v247, 31, v235
	v_bfi_b32 v235, v247, v235, v246
	v_cndmask_b32_e32 v235, -1, v235, vcc
	v_max_u32_e32 v246, v249, v235
	v_min_u32_e32 v249, v249, v235
	v_min_u32_e32 v137, v137, v246
	v_cmp_lt_i32_e32 vcc, 0x1f00, v138
	v_xor_b32_e32 v240, 0x7fffffff, v236
	v_ashrrev_i32_e32 v241, 31, v236
	v_bfi_b32 v236, v241, v236, v240
	v_cndmask_b32_e32 v236, -1, v236, vcc
	v_max_u32_e32 v240, v150, v236
	v_min_u32_e32 v150, v150, v236
	v_min_u32_e32 v151, v151, v240
	v_cmp_lt_i32_e32 vcc, 0x1f40, v138
	v_xor_b32_e32 v242, 0x7fffffff, v237
	v_ashrrev_i32_e32 v243, 31, v237
	v_bfi_b32 v237, v243, v237, v242
	v_cndmask_b32_e32 v237, -1, v237, vcc
	v_max_u32_e32 v242, v249, v237
	v_min_u32_e32 v249, v249, v237
	v_min_u32_e32 v137, v137, v242
	v_cmp_lt_i32_e32 vcc, 0x1f80, v138
	v_xor_b32_e32 v244, 0x7fffffff, v238
	v_ashrrev_i32_e32 v245, 31, v238
	v_bfi_b32 v238, v245, v238, v244
	v_cndmask_b32_e32 v238, -1, v238, vcc
	v_max_u32_e32 v244, v150, v238
	v_min_u32_e32 v150, v150, v238
	v_min_u32_e32 v151, v151, v244
	v_cmp_lt_i32_e32 vcc, 0x1fc0, v138
	v_xor_b32_e32 v246, 0x7fffffff, v239
	v_ashrrev_i32_e32 v247, 31, v239
	v_bfi_b32 v239, v247, v239, v246
	v_cndmask_b32_e32 v239, -1, v239, vcc
	v_max_u32_e32 v246, v249, v239
	v_min_u32_e32 v249, v249, v239
	v_min_u32_e32 v137, v137, v246
.Lsel_cv_next7:
.Lsel_cv_done:
	v_max_u32_e32 v137, v137, v151
	v_xor_b32_e32 v240, 1, v131
	v_lshlrev_b32_e32 v240, 2, v240
	ds_bpermute_b32 v241, v240, v137
	s_waitcnt lgkmcnt(0)
	v_max_u32_e32 v137, v137, v241
	v_xor_b32_e32 v240, 2, v131
	v_lshlrev_b32_e32 v240, 2, v240
	ds_bpermute_b32 v241, v240, v137
	s_waitcnt lgkmcnt(0)
	v_max_u32_e32 v137, v137, v241
	v_xor_b32_e32 v240, 4, v131
	v_lshlrev_b32_e32 v240, 2, v240
	ds_bpermute_b32 v241, v240, v137
	s_waitcnt lgkmcnt(0)
	v_max_u32_e32 v137, v137, v241
	v_xor_b32_e32 v240, 8, v131
	v_lshlrev_b32_e32 v240, 2, v240
	ds_bpermute_b32 v241, v240, v137
	s_waitcnt lgkmcnt(0)
	v_max_u32_e32 v137, v137, v241
	v_xor_b32_e32 v240, 16, v131
	v_lshlrev_b32_e32 v240, 2, v240
	ds_bpermute_b32 v241, v240, v137
	s_waitcnt lgkmcnt(0)
	v_max_u32_e32 v137, v137, v241
	v_xor_b32_e32 v240, 32, v131
	v_lshlrev_b32_e32 v240, 2, v240
	ds_bpermute_b32 v241, v240, v137
	s_waitcnt lgkmcnt(0)
	v_max_u32_e32 v137, v137, v241
	s_nop 0
	v_readfirstlane_b32 s86, v137
	s_add_u32 s86, s86, 1
	s_movk_i32 s56, 0x100
	s_mov_b32 s57, 0
	s_mov_b32 s87, 21
	s_mov_b32 s88, 0
.Lsel_pass:
	v_mov_b32_e32 v240, 0
	v_mov_b32_e32 v241, 0
	v_mov_b32_e32 v242, 0
	v_mov_b32_e32 v243, 0
	v_lshl_add_u32 v140, v131, 4, v136
	ds_write_b128 v140, v[240:243]
	ds_write_b128 v140, v[240:243] offset:1024
	ds_write_b128 v140, v[240:243] offset:2048
	ds_write_b128 v140, v[240:243] offset:3072
	ds_write_b128 v140, v[240:243] offset:4096
	ds_write_b128 v140, v[240:243] offset:5120
	ds_write_b128 v140, v[240:243] offset:6144
	ds_write_b128 v140, v[240:243] offset:7168
	s_waitcnt lgkmcnt(0)
	s_cmp_eq_u32 s88, 2
	s_cbranch_scc0 .Lsel_histm
	v_xor_b32_e32 v240, s57, v0
	v_cmp_gt_u32_e32 vcc, s86, v240
	s_cbranch_vccz .Lsel_h2s0
	s_mov_b64 exec, vcc
	v_lshl_add_u32 v241, v240, 2, v136
	ds_add_u32 v241, v135
	s_mov_b64 exec, -1
.Lsel_h2s0:
	v_xor_b32_e32 v242, s57, v1
	v_cmp_gt_u32_e32 vcc, s86, v242
	s_cbranch_vccz .Lsel_h2s1
	s_mov_b64 exec, vcc
	v_lshl_add_u32 v243, v242, 2, v136
	ds_add_u32 v243, v135
	s_mov_b64 exec, -1
.Lsel_h2s1:
	v_xor_b32_e32 v244, s57, v2
	v_cmp_gt_u32_e32 vcc, s86, v244
	s_cbranch_vccz .Lsel_h2s2
	s_mov_b64 exec, vcc
	v_lshl_add_u32 v245, v244, 2, v136
	ds_add_u32 v245, v135
	s_mov_b64 exec, -1
.Lsel_h2s2:
	v_xor_b32_e32 v246, s57, v3
	v_cmp_gt_u32_e32 vcc, s86, v246
	s_cbranch_vccz .Lsel_h2s3
	s_mov_b64 exec, vcc
	v_lshl_add_u32 v247, v246, 2, v136
	ds_add_u32 v247, v135
	s_mov_b64 exec, -1
.Lsel_h2s3:
	v_xor_b32_e32 v240, s57, v4
	v_cmp_gt_u32_e32 vcc, s86, v240
	s_cbranch_vccz .Lsel_h2s4
	s_mov_b64 exec, vcc
	v_lshl_add_u32 v241, v240, 2, v136
	ds_add_u32 v241, v135
	s_mov_b64 exec, -1
.Lsel_h2s4:
	v_xor_b32_e32 v242, s57, v5
	v_cmp_gt_u32_e32 vcc, s86, v242
	s_cbranch_vccz .Lsel_h2s5
	s_mov_b64 exec, vcc
	v_lshl_add_u32 v243, v242, 2, v136
	ds_add_u32 v243, v135
	s_mov_b64 exec, -1
.Lsel_h2s5:
	v_xor_b32_e32 v244, s57, v6
	v_cmp_gt_u32_e32 vcc, s86, v244
	s_cbranch_vccz .Lsel_h2s6
	s_mov_b64 exec, vcc
	v_lshl_add_u32 v245, v244, 2, v136
	ds_add_u32 v245, v135
	s_mov_b64 exec, -1
.Lsel_h2s6:
	v_xor_b32_e32 v246, s57, v7
	v_cmp_gt_u32_e32 vcc, s86, v246
	s_cbranch_vccz .Lsel_h2s7
	s_mov_b64 exec, vcc
	v_lshl_add_u32 v247, v246, 2, v136
	ds_add_u32 v247, v135
	s_mov_b64 exec, -1
.Lsel_h2s7:
	v_xor_b32_e32 v240, s57, v8
	v_cmp_gt_u32_e32 vcc, s86, v240
	s_cbranch_vccz .Lsel_h2s8
	s_mov_b64 exec, vcc
	v_lshl_add_u32 v241, v240, 2, v136
	ds_add_u32 v241, v135
	s_mov_b64 exec, -1
.Lsel_h2s8:
	v_xor_b32_e32 v242, s57, v9
	v_cmp_gt_u32_e32 vcc, s86, v242
	s_cbranch_vccz .Lsel_h2s9
	s_mov_b64 exec, vcc
	v_lshl_add_u32 v243, v242, 2, v136
	ds_add_u32 v243, v135
	s_mov_b64 exec, -1
.Lsel_h2s9:
	v_xor_b32_e32 v244, s57, v10
	v_cmp_gt_u32_e32 vcc, s86, v244
	s_cbranch_vccz .Lsel_h2s10
	s_mov_b64 exec, vcc
	v_lshl_add_u32 v245, v244, 2, v136
	ds_add_u32 v245, v135
	s_mov_b64 exec, -1
.Lsel_h2s10:
	v_xor_b32_e32 v246, s57, v11
	v_cmp_gt_u32_e32 vcc, s86, v246
	s_cbranch_vccz .Lsel_h2s11
	s_mov_b64 exec, vcc
	v_lshl_add_u32 v247, v246, 2, v136
	ds_add_u32 v247, v135
	s_mov_b64 exec, -1
.Lsel_h2s11:
	v_xor_b32_e32 v240, s57, v12
	v_cmp_gt_u32_e32 vcc, s86, v240
	s_cbranch_vccz .Lsel_h2s12
	s_mov_b64 exec, vcc
	v_lshl_add_u32 v241, v240, 2, v136
	ds_add_u32 v241, v135
	s_mov_b64 exec, -1
.Lsel_h2s12:
	v_xor_b32_e32 v242, s57, v13
	v_cmp_gt_u32_e32 vcc, s86, v242
	s_cbranch_vccz .Lsel_h2s13
	s_mov_b64 exec, vcc
	v_lshl_add_u32 v243, v242, 2, v136
	ds_add_u32 v243, v135
	s_mov_b64 exec, -1
.Lsel_h2s13:
	v_xor_b32_e32 v244, s57, v14
	v_cmp_gt_u32_e32 vcc, s86, v244
	s_cbranch_vccz .Lsel_h2s14
	s_mov_b64 exec, vcc
	v_lshl_add_u32 v245, v244, 2, v136
	ds_add_u32 v245, v135
	s_mov_b64 exec, -1
.Lsel_h2s14:
	v_xor_b32_e32 v246, s57, v15
	v_cmp_gt_u32_e32 vcc, s86, v246
	s_cbranch_vccz .Lsel_h2s15
	s_mov_b64 exec, vcc
	v_lshl_add_u32 v247, v246, 2, v136
	ds_add_u32 v247, v135
	s_mov_b64 exec, -1
.Lsel_h2s15:
	s_cmpk_le_u32 s34, 16
	s_cbranch_scc1 .Lsel_hist_done
	v_xor_b32_e32 v240, s57, v16
	v_cmp_gt_u32_e32 vcc, s86, v240
	s_cbranch_vccz .Lsel_h2s16
	s_mov_b64 exec, vcc
	v_lshl_add_u32 v241, v240, 2, v136
	ds_add_u32 v241, v135
	s_mov_b64 exec, -1
.Lsel_h2s16:
	v_xor_b32_e32 v242, s57, v17
	v_cmp_gt_u32_e32 vcc, s86, v242
	s_cbranch_vccz .Lsel_h2s17
	s_mov_b64 exec, vcc
	v_lshl_add_u32 v243, v242, 2, v136
	ds_add_u32 v243, v135
	s_mov_b64 exec, -1
.Lsel_h2s17:
	v_xor_b32_e32 v244, s57, v18
	v_cmp_gt_u32_e32 vcc, s86, v244
	s_cbranch_vccz .Lsel_h2s18
	s_mov_b64 exec, vcc
	v_lshl_add_u32 v245, v244, 2, v136
	ds_add_u32 v245, v135
	s_mov_b64 exec, -1
.Lsel_h2s18:
	v_xor_b32_e32 v246, s57, v19
	v_cmp_gt_u32_e32 vcc, s86, v246
	s_cbranch_vccz .Lsel_h2s19
	s_mov_b64 exec, vcc
	v_lshl_add_u32 v247, v246, 2, v136
	ds_add_u32 v247, v135
	s_mov_b64 exec, -1
.Lsel_h2s19:
	v_xor_b32_e32 v240, s57, v20
	v_cmp_gt_u32_e32 vcc, s86, v240
	s_cbranch_vccz .Lsel_h2s20
	s_mov_b64 exec, vcc
	v_lshl_add_u32 v241, v240, 2, v136
	ds_add_u32 v241, v135
	s_mov_b64 exec, -1
.Lsel_h2s20:
	v_xor_b32_e32 v242, s57, v21
	v_cmp_gt_u32_e32 vcc, s86, v242
	s_cbranch_vccz .Lsel_h2s21
	s_mov_b64 exec, vcc
	v_lshl_add_u32 v243, v242, 2, v136
	ds_add_u32 v243, v135
	s_mov_b64 exec, -1
.Lsel_h2s21:
	v_xor_b32_e32 v244, s57, v22
	v_cmp_gt_u32_e32 vcc, s86, v244
	s_cbranch_vccz .Lsel_h2s22
	s_mov_b64 exec, vcc
	v_lshl_add_u32 v245, v244, 2, v136
	ds_add_u32 v245, v135
	s_mov_b64 exec, -1
.Lsel_h2s22:
	v_xor_b32_e32 v246, s57, v23
	v_cmp_gt_u32_e32 vcc, s86, v246
	s_cbranch_vccz .Lsel_h2s23
	s_mov_b64 exec, vcc
	v_lshl_add_u32 v247, v246, 2, v136
	ds_add_u32 v247, v135
	s_mov_b64 exec, -1
.Lsel_h2s23:
	v_xor_b32_e32 v240, s57, v24
	v_cmp_gt_u32_e32 vcc, s86, v240
	s_cbranch_vccz .Lsel_h2s24
	s_mov_b64 exec, vcc
	v_lshl_add_u32 v241, v240, 2, v136
	ds_add_u32 v241, v135
	s_mov_b64 exec, -1
.Lsel_h2s24:
	v_xor_b32_e32 v242, s57, v25
	v_cmp_gt_u32_e32 vcc, s86, v242
	s_cbranch_vccz .Lsel_h2s25
	s_mov_b64 exec, vcc
	v_lshl_add_u32 v243, v242, 2, v136
	ds_add_u32 v243, v135
	s_mov_b64 exec, -1
.Lsel_h2s25:
	v_xor_b32_e32 v244, s57, v26
	v_cmp_gt_u32_e32 vcc, s86, v244
	s_cbranch_vccz .Lsel_h2s26
	s_mov_b64 exec, vcc
	v_lshl_add_u32 v245, v244, 2, v136
	ds_add_u32 v245, v135
	s_mov_b64 exec, -1
.Lsel_h2s26:
	v_xor_b32_e32 v246, s57, v27
	v_cmp_gt_u32_e32 vcc, s86, v246
	s_cbranch_vccz .Lsel_h2s27
	s_mov_b64 exec, vcc
	v_lshl_add_u32 v247, v246, 2, v136
	ds_add_u32 v247, v135
	s_mov_b64 exec, -1
.Lsel_h2s27:
	v_xor_b32_e32 v240, s57, v28
	v_cmp_gt_u32_e32 vcc, s86, v240
	s_cbranch_vccz .Lsel_h2s28
	s_mov_b64 exec, vcc
	v_lshl_add_u32 v241, v240, 2, v136
	ds_add_u32 v241, v135
	s_mov_b64 exec, -1
.Lsel_h2s28:
	v_xor_b32_e32 v242, s57, v29
	v_cmp_gt_u32_e32 vcc, s86, v242
	s_cbranch_vccz .Lsel_h2s29
	s_mov_b64 exec, vcc
	v_lshl_add_u32 v243, v242, 2, v136
	ds_add_u32 v243, v135
	s_mov_b64 exec, -1
.Lsel_h2s29:
	v_xor_b32_e32 v244, s57, v30
	v_cmp_gt_u32_e32 vcc, s86, v244
	s_cbranch_vccz .Lsel_h2s30
	s_mov_b64 exec, vcc
	v_lshl_add_u32 v245, v244, 2, v136
	ds_add_u32 v245, v135
	s_mov_b64 exec, -1
.Lsel_h2s30:
	v_xor_b32_e32 v246, s57, v31
	v_cmp_gt_u32_e32 vcc, s86, v246
	s_cbranch_vccz .Lsel_h2s31
	s_mov_b64 exec, vcc
	v_lshl_add_u32 v247, v246, 2, v136
	ds_add_u32 v247, v135
	s_mov_b64 exec, -1
.Lsel_h2s31:
	s_cmpk_le_u32 s34, 32
	s_cbranch_scc1 .Lsel_hist_done
	v_xor_b32_e32 v240, s57, v32
	v_cmp_gt_u32_e32 vcc, s86, v240
	s_cbranch_vccz .Lsel_h2s32
	s_mov_b64 exec, vcc
	v_lshl_add_u32 v241, v240, 2, v136
	ds_add_u32 v241, v135
	s_mov_b64 exec, -1
.Lsel_h2s32:
	v_xor_b32_e32 v242, s57, v33
	v_cmp_gt_u32_e32 vcc, s86, v242
	s_cbranch_vccz .Lsel_h2s33
	s_mov_b64 exec, vcc
	v_lshl_add_u32 v243, v242, 2, v136
	ds_add_u32 v243, v135
	s_mov_b64 exec, -1
.Lsel_h2s33:
	v_xor_b32_e32 v244, s57, v34
	v_cmp_gt_u32_e32 vcc, s86, v244
	s_cbranch_vccz .Lsel_h2s34
	s_mov_b64 exec, vcc
	v_lshl_add_u32 v245, v244, 2, v136
	ds_add_u32 v245, v135
	s_mov_b64 exec, -1
.Lsel_h2s34:
	v_xor_b32_e32 v246, s57, v35
	v_cmp_gt_u32_e32 vcc, s86, v246
	s_cbranch_vccz .Lsel_h2s35
	s_mov_b64 exec, vcc
	v_lshl_add_u32 v247, v246, 2, v136
	ds_add_u32 v247, v135
	s_mov_b64 exec, -1
.Lsel_h2s35:
	v_xor_b32_e32 v240, s57, v36
	v_cmp_gt_u32_e32 vcc, s86, v240
	s_cbranch_vccz .Lsel_h2s36
	s_mov_b64 exec, vcc
	v_lshl_add_u32 v241, v240, 2, v136
	ds_add_u32 v241, v135
	s_mov_b64 exec, -1
.Lsel_h2s36:
	v_xor_b32_e32 v242, s57, v37
	v_cmp_gt_u32_e32 vcc, s86, v242
	s_cbranch_vccz .Lsel_h2s37
	s_mov_b64 exec, vcc
	v_lshl_add_u32 v243, v242, 2, v136
	ds_add_u32 v243, v135
	s_mov_b64 exec, -1
.Lsel_h2s37:
	v_xor_b32_e32 v244, s57, v38
	v_cmp_gt_u32_e32 vcc, s86, v244
	s_cbranch_vccz .Lsel_h2s38
	s_mov_b64 exec, vcc
	v_lshl_add_u32 v245, v244, 2, v136
	ds_add_u32 v245, v135
	s_mov_b64 exec, -1
.Lsel_h2s38:
	v_xor_b32_e32 v246, s57, v39
	v_cmp_gt_u32_e32 vcc, s86, v246
	s_cbranch_vccz .Lsel_h2s39
	s_mov_b64 exec, vcc
	v_lshl_add_u32 v247, v246, 2, v136
	ds_add_u32 v247, v135
	s_mov_b64 exec, -1
.Lsel_h2s39:
	v_xor_b32_e32 v240, s57, v40
	v_cmp_gt_u32_e32 vcc, s86, v240
	s_cbranch_vccz .Lsel_h2s40
	s_mov_b64 exec, vcc
	v_lshl_add_u32 v241, v240, 2, v136
	ds_add_u32 v241, v135
	s_mov_b64 exec, -1
.Lsel_h2s40:
	v_xor_b32_e32 v242, s57, v41
	v_cmp_gt_u32_e32 vcc, s86, v242
	s_cbranch_vccz .Lsel_h2s41
	s_mov_b64 exec, vcc
	v_lshl_add_u32 v243, v242, 2, v136
	ds_add_u32 v243, v135
	s_mov_b64 exec, -1
.Lsel_h2s41:
	v_xor_b32_e32 v244, s57, v42
	v_cmp_gt_u32_e32 vcc, s86, v244
	s_cbranch_vccz .Lsel_h2s42
	s_mov_b64 exec, vcc
	v_lshl_add_u32 v245, v244, 2, v136
	ds_add_u32 v245, v135
	s_mov_b64 exec, -1
.Lsel_h2s42:
	v_xor_b32_e32 v246, s57, v43
	v_cmp_gt_u32_e32 vcc, s86, v246
	s_cbranch_vccz .Lsel_h2s43
	s_mov_b64 exec, vcc
	v_lshl_add_u32 v247, v246, 2, v136
	ds_add_u32 v247, v135
	s_mov_b64 exec, -1
.Lsel_h2s43:
	v_xor_b32_e32 v240, s57, v44
	v_cmp_gt_u32_e32 vcc, s86, v240
	s_cbranch_vccz .Lsel_h2s44
	s_mov_b64 exec, vcc
	v_lshl_add_u32 v241, v240, 2, v136
	ds_add_u32 v241, v135
	s_mov_b64 exec, -1
.Lsel_h2s44:
	v_xor_b32_e32 v242, s57, v45
	v_cmp_gt_u32_e32 vcc, s86, v242
	s_cbranch_vccz .Lsel_h2s45
	s_mov_b64 exec, vcc
	v_lshl_add_u32 v243, v242, 2, v136
	ds_add_u32 v243, v135
	s_mov_b64 exec, -1
.Lsel_h2s45:
	v_xor_b32_e32 v244, s57, v46
	v_cmp_gt_u32_e32 vcc, s86, v244
	s_cbranch_vccz .Lsel_h2s46
	s_mov_b64 exec, vcc
	v_lshl_add_u32 v245, v244, 2, v136
	ds_add_u32 v245, v135
	s_mov_b64 exec, -1
.Lsel_h2s46:
	v_xor_b32_e32 v246, s57, v47
	v_cmp_gt_u32_e32 vcc, s86, v246
	s_cbranch_vccz .Lsel_h2s47
	s_mov_b64 exec, vcc
	v_lshl_add_u32 v247, v246, 2, v136
	ds_add_u32 v247, v135
	s_mov_b64 exec, -1
.Lsel_h2s47:
	s_cmpk_le_u32 s34, 48
	s_cbranch_scc1 .Lsel_hist_done
	v_xor_b32_e32 v240, s57, v48
	v_cmp_gt_u32_e32 vcc, s86, v240
	s_cbranch_vccz .Lsel_h2s48
	s_mov_b64 exec, vcc
	v_lshl_add_u32 v241, v240, 2, v136
	ds_add_u32 v241, v135
	s_mov_b64 exec, -1
.Lsel_h2s48:
	v_xor_b32_e32 v242, s57, v49
	v_cmp_gt_u32_e32 vcc, s86, v242
	s_cbranch_vccz .Lsel_h2s49
	s_mov_b64 exec, vcc
	v_lshl_add_u32 v243, v242, 2, v136
	ds_add_u32 v243, v135
	s_mov_b64 exec, -1
.Lsel_h2s49:
	v_xor_b32_e32 v244, s57, v50
	v_cmp_gt_u32_e32 vcc, s86, v244
	s_cbranch_vccz .Lsel_h2s50
	s_mov_b64 exec, vcc
	v_lshl_add_u32 v245, v244, 2, v136
	ds_add_u32 v245, v135
	s_mov_b64 exec, -1
.Lsel_h2s50:
	v_xor_b32_e32 v246, s57, v51
	v_cmp_gt_u32_e32 vcc, s86, v246
	s_cbranch_vccz .Lsel_h2s51
	s_mov_b64 exec, vcc
	v_lshl_add_u32 v247, v246, 2, v136
	ds_add_u32 v247, v135
	s_mov_b64 exec, -1
.Lsel_h2s51:
	v_xor_b32_e32 v240, s57, v52
	v_cmp_gt_u32_e32 vcc, s86, v240
	s_cbranch_vccz .Lsel_h2s52
	s_mov_b64 exec, vcc
	v_lshl_add_u32 v241, v240, 2, v136
	ds_add_u32 v241, v135
	s_mov_b64 exec, -1
.Lsel_h2s52:
	v_xor_b32_e32 v242, s57, v53
	v_cmp_gt_u32_e32 vcc, s86, v242
	s_cbranch_vccz .Lsel_h2s53
	s_mov_b64 exec, vcc
	v_lshl_add_u32 v243, v242, 2, v136
	ds_add_u32 v243, v135
	s_mov_b64 exec, -1
.Lsel_h2s53:
	v_xor_b32_e32 v244, s57, v54
	v_cmp_gt_u32_e32 vcc, s86, v244
	s_cbranch_vccz .Lsel_h2s54
	s_mov_b64 exec, vcc
	v_lshl_add_u32 v245, v244, 2, v136
	ds_add_u32 v245, v135
	s_mov_b64 exec, -1
.Lsel_h2s54:
	v_xor_b32_e32 v246, s57, v55
	v_cmp_gt_u32_e32 vcc, s86, v246
	s_cbranch_vccz .Lsel_h2s55
	s_mov_b64 exec, vcc
	v_lshl_add_u32 v247, v246, 2, v136
	ds_add_u32 v247, v135
	s_mov_b64 exec, -1
.Lsel_h2s55:
	v_xor_b32_e32 v240, s57, v56
	v_cmp_gt_u32_e32 vcc, s86, v240
	s_cbranch_vccz .Lsel_h2s56
	s_mov_b64 exec, vcc
	v_lshl_add_u32 v241, v240, 2, v136
	ds_add_u32 v241, v135
	s_mov_b64 exec, -1
.Lsel_h2s56:
	v_xor_b32_e32 v242, s57, v57
	v_cmp_gt_u32_e32 vcc, s86, v242
	s_cbranch_vccz .Lsel_h2s57
	s_mov_b64 exec, vcc
	v_lshl_add_u32 v243, v242, 2, v136
	ds_add_u32 v243, v135
	s_mov_b64 exec, -1
.Lsel_h2s57:
	v_xor_b32_e32 v244, s57, v58
	v_cmp_gt_u32_e32 vcc, s86, v244
	s_cbranch_vccz .Lsel_h2s58
	s_mov_b64 exec, vcc
	v_lshl_add_u32 v245, v244, 2, v136
	ds_add_u32 v245, v135
	s_mov_b64 exec, -1
.Lsel_h2s58:
	v_xor_b32_e32 v246, s57, v59
	v_cmp_gt_u32_e32 vcc, s86, v246
	s_cbranch_vccz .Lsel_h2s59
	s_mov_b64 exec, vcc
	v_lshl_add_u32 v247, v246, 2, v136
	ds_add_u32 v247, v135
	s_mov_b64 exec, -1
.Lsel_h2s59:
	v_xor_b32_e32 v240, s57, v60
	v_cmp_gt_u32_e32 vcc, s86, v240
	s_cbranch_vccz .Lsel_h2s60
	s_mov_b64 exec, vcc
	v_lshl_add_u32 v241, v240, 2, v136
	ds_add_u32 v241, v135
	s_mov_b64 exec, -1
.Lsel_h2s60:
	v_xor_b32_e32 v242, s57, v61
	v_cmp_gt_u32_e32 vcc, s86, v242
	s_cbranch_vccz .Lsel_h2s61
	s_mov_b64 exec, vcc
	v_lshl_add_u32 v243, v242, 2, v136
	ds_add_u32 v243, v135
	s_mov_b64 exec, -1
.Lsel_h2s61:
	v_xor_b32_e32 v244, s57, v62
	v_cmp_gt_u32_e32 vcc, s86, v244
	s_cbranch_vccz .Lsel_h2s62
	s_mov_b64 exec, vcc
	v_lshl_add_u32 v245, v244, 2, v136
	ds_add_u32 v245, v135
	s_mov_b64 exec, -1
.Lsel_h2s62:
	v_xor_b32_e32 v246, s57, v63
	v_cmp_gt_u32_e32 vcc, s86, v246
	s_cbranch_vccz .Lsel_h2s63
	s_mov_b64 exec, vcc
	v_lshl_add_u32 v247, v246, 2, v136
	ds_add_u32 v247, v135
	s_mov_b64 exec, -1
.Lsel_h2s63:
	s_cmpk_le_u32 s34, 64
	s_cbranch_scc1 .Lsel_hist_done
	v_xor_b32_e32 v240, s57, v64
	v_cmp_gt_u32_e32 vcc, s86, v240
	s_cbranch_vccz .Lsel_h2s64
	s_mov_b64 exec, vcc
	v_lshl_add_u32 v241, v240, 2, v136
	ds_add_u32 v241, v135
	s_mov_b64 exec, -1
.Lsel_h2s64:
	v_xor_b32_e32 v242, s57, v65
	v_cmp_gt_u32_e32 vcc, s86, v242
	s_cbranch_vccz .Lsel_h2s65
	s_mov_b64 exec, vcc
	v_lshl_add_u32 v243, v242, 2, v136
	ds_add_u32 v243, v135
	s_mov_b64 exec, -1
.Lsel_h2s65:
	v_xor_b32_e32 v244, s57, v66
	v_cmp_gt_u32_e32 vcc, s86, v244
	s_cbranch_vccz .Lsel_h2s66
	s_mov_b64 exec, vcc
	v_lshl_add_u32 v245, v244, 2, v136
	ds_add_u32 v245, v135
	s_mov_b64 exec, -1
.Lsel_h2s66:
	v_xor_b32_e32 v246, s57, v67
	v_cmp_gt_u32_e32 vcc, s86, v246
	s_cbranch_vccz .Lsel_h2s67
	s_mov_b64 exec, vcc
	v_lshl_add_u32 v247, v246, 2, v136
	ds_add_u32 v247, v135
	s_mov_b64 exec, -1
.Lsel_h2s67:
	v_xor_b32_e32 v240, s57, v68
	v_cmp_gt_u32_e32 vcc, s86, v240
	s_cbranch_vccz .Lsel_h2s68
	s_mov_b64 exec, vcc
	v_lshl_add_u32 v241, v240, 2, v136
	ds_add_u32 v241, v135
	s_mov_b64 exec, -1
.Lsel_h2s68:
	v_xor_b32_e32 v242, s57, v69
	v_cmp_gt_u32_e32 vcc, s86, v242
	s_cbranch_vccz .Lsel_h2s69
	s_mov_b64 exec, vcc
	v_lshl_add_u32 v243, v242, 2, v136
	ds_add_u32 v243, v135
	s_mov_b64 exec, -1
.Lsel_h2s69:
	v_xor_b32_e32 v244, s57, v70
	v_cmp_gt_u32_e32 vcc, s86, v244
	s_cbranch_vccz .Lsel_h2s70
	s_mov_b64 exec, vcc
	v_lshl_add_u32 v245, v244, 2, v136
	ds_add_u32 v245, v135
	s_mov_b64 exec, -1
.Lsel_h2s70:
	v_xor_b32_e32 v246, s57, v71
	v_cmp_gt_u32_e32 vcc, s86, v246
	s_cbranch_vccz .Lsel_h2s71
	s_mov_b64 exec, vcc
	v_lshl_add_u32 v247, v246, 2, v136
	ds_add_u32 v247, v135
	s_mov_b64 exec, -1
.Lsel_h2s71:
	v_xor_b32_e32 v240, s57, v72
	v_cmp_gt_u32_e32 vcc, s86, v240
	s_cbranch_vccz .Lsel_h2s72
	s_mov_b64 exec, vcc
	v_lshl_add_u32 v241, v240, 2, v136
	ds_add_u32 v241, v135
	s_mov_b64 exec, -1
.Lsel_h2s72:
	v_xor_b32_e32 v242, s57, v73
	v_cmp_gt_u32_e32 vcc, s86, v242
	s_cbranch_vccz .Lsel_h2s73
	s_mov_b64 exec, vcc
	v_lshl_add_u32 v243, v242, 2, v136
	ds_add_u32 v243, v135
	s_mov_b64 exec, -1
.Lsel_h2s73:
	v_xor_b32_e32 v244, s57, v74
	v_cmp_gt_u32_e32 vcc, s86, v244
	s_cbranch_vccz .Lsel_h2s74
	s_mov_b64 exec, vcc
	v_lshl_add_u32 v245, v244, 2, v136
	ds_add_u32 v245, v135
	s_mov_b64 exec, -1
.Lsel_h2s74:
	v_xor_b32_e32 v246, s57, v75
	v_cmp_gt_u32_e32 vcc, s86, v246
	s_cbranch_vccz .Lsel_h2s75
	s_mov_b64 exec, vcc
	v_lshl_add_u32 v247, v246, 2, v136
	ds_add_u32 v247, v135
	s_mov_b64 exec, -1
.Lsel_h2s75:
	v_xor_b32_e32 v240, s57, v76
	v_cmp_gt_u32_e32 vcc, s86, v240
	s_cbranch_vccz .Lsel_h2s76
	s_mov_b64 exec, vcc
	v_lshl_add_u32 v241, v240, 2, v136
	ds_add_u32 v241, v135
	s_mov_b64 exec, -1
.Lsel_h2s76:
	v_xor_b32_e32 v242, s57, v77
	v_cmp_gt_u32_e32 vcc, s86, v242
	s_cbranch_vccz .Lsel_h2s77
	s_mov_b64 exec, vcc
	v_lshl_add_u32 v243, v242, 2, v136
	ds_add_u32 v243, v135
	s_mov_b64 exec, -1
.Lsel_h2s77:
	v_xor_b32_e32 v244, s57, v78
	v_cmp_gt_u32_e32 vcc, s86, v244
	s_cbranch_vccz .Lsel_h2s78
	s_mov_b64 exec, vcc
	v_lshl_add_u32 v245, v244, 2, v136
	ds_add_u32 v245, v135
	s_mov_b64 exec, -1
.Lsel_h2s78:
	v_xor_b32_e32 v246, s57, v79
	v_cmp_gt_u32_e32 vcc, s86, v246
	s_cbranch_vccz .Lsel_h2s79
	s_mov_b64 exec, vcc
	v_lshl_add_u32 v247, v246, 2, v136
	ds_add_u32 v247, v135
	s_mov_b64 exec, -1
.Lsel_h2s79:
	s_cmpk_le_u32 s34, 80
	s_cbranch_scc1 .Lsel_hist_done
	v_xor_b32_e32 v240, s57, v80
	v_cmp_gt_u32_e32 vcc, s86, v240
	s_cbranch_vccz .Lsel_h2s80
	s_mov_b64 exec, vcc
	v_lshl_add_u32 v241, v240, 2, v136
	ds_add_u32 v241, v135
	s_mov_b64 exec, -1
.Lsel_h2s80:
	v_xor_b32_e32 v242, s57, v81
	v_cmp_gt_u32_e32 vcc, s86, v242
	s_cbranch_vccz .Lsel_h2s81
	s_mov_b64 exec, vcc
	v_lshl_add_u32 v243, v242, 2, v136
	ds_add_u32 v243, v135
	s_mov_b64 exec, -1
.Lsel_h2s81:
	v_xor_b32_e32 v244, s57, v82
	v_cmp_gt_u32_e32 vcc, s86, v244
	s_cbranch_vccz .Lsel_h2s82
	s_mov_b64 exec, vcc
	v_lshl_add_u32 v245, v244, 2, v136
	ds_add_u32 v245, v135
	s_mov_b64 exec, -1
.Lsel_h2s82:
	v_xor_b32_e32 v246, s57, v83
	v_cmp_gt_u32_e32 vcc, s86, v246
	s_cbranch_vccz .Lsel_h2s83
	s_mov_b64 exec, vcc
	v_lshl_add_u32 v247, v246, 2, v136
	ds_add_u32 v247, v135
	s_mov_b64 exec, -1
.Lsel_h2s83:
	v_xor_b32_e32 v240, s57, v84
	v_cmp_gt_u32_e32 vcc, s86, v240
	s_cbranch_vccz .Lsel_h2s84
	s_mov_b64 exec, vcc
	v_lshl_add_u32 v241, v240, 2, v136
	ds_add_u32 v241, v135
	s_mov_b64 exec, -1
.Lsel_h2s84:
	v_xor_b32_e32 v242, s57, v85
	v_cmp_gt_u32_e32 vcc, s86, v242
	s_cbranch_vccz .Lsel_h2s85
	s_mov_b64 exec, vcc
	v_lshl_add_u32 v243, v242, 2, v136
	ds_add_u32 v243, v135
	s_mov_b64 exec, -1
.Lsel_h2s85:
	v_xor_b32_e32 v244, s57, v86
	v_cmp_gt_u32_e32 vcc, s86, v244
	s_cbranch_vccz .Lsel_h2s86
	s_mov_b64 exec, vcc
	v_lshl_add_u32 v245, v244, 2, v136
	ds_add_u32 v245, v135
	s_mov_b64 exec, -1
.Lsel_h2s86:
	v_xor_b32_e32 v246, s57, v87
	v_cmp_gt_u32_e32 vcc, s86, v246
	s_cbranch_vccz .Lsel_h2s87
	s_mov_b64 exec, vcc
	v_lshl_add_u32 v247, v246, 2, v136
	ds_add_u32 v247, v135
	s_mov_b64 exec, -1
.Lsel_h2s87:
	v_xor_b32_e32 v240, s57, v88
	v_cmp_gt_u32_e32 vcc, s86, v240
	s_cbranch_vccz .Lsel_h2s88
	s_mov_b64 exec, vcc
	v_lshl_add_u32 v241, v240, 2, v136
	ds_add_u32 v241, v135
	s_mov_b64 exec, -1
.Lsel_h2s88:
	v_xor_b32_e32 v242, s57, v89
	v_cmp_gt_u32_e32 vcc, s86, v242
	s_cbranch_vccz .Lsel_h2s89
	s_mov_b64 exec, vcc
	v_lshl_add_u32 v243, v242, 2, v136
	ds_add_u32 v243, v135
	s_mov_b64 exec, -1
.Lsel_h2s89:
	v_xor_b32_e32 v244, s57, v90
	v_cmp_gt_u32_e32 vcc, s86, v244
	s_cbranch_vccz .Lsel_h2s90
	s_mov_b64 exec, vcc
	v_lshl_add_u32 v245, v244, 2, v136
	ds_add_u32 v245, v135
	s_mov_b64 exec, -1
.Lsel_h2s90:
	v_xor_b32_e32 v246, s57, v91
	v_cmp_gt_u32_e32 vcc, s86, v246
	s_cbranch_vccz .Lsel_h2s91
	s_mov_b64 exec, vcc
	v_lshl_add_u32 v247, v246, 2, v136
	ds_add_u32 v247, v135
	s_mov_b64 exec, -1
.Lsel_h2s91:
	v_xor_b32_e32 v240, s57, v92
	v_cmp_gt_u32_e32 vcc, s86, v240
	s_cbranch_vccz .Lsel_h2s92
	s_mov_b64 exec, vcc
	v_lshl_add_u32 v241, v240, 2, v136
	ds_add_u32 v241, v135
	s_mov_b64 exec, -1
.Lsel_h2s92:
	v_xor_b32_e32 v242, s57, v93
	v_cmp_gt_u32_e32 vcc, s86, v242
	s_cbranch_vccz .Lsel_h2s93
	s_mov_b64 exec, vcc
	v_lshl_add_u32 v243, v242, 2, v136
	ds_add_u32 v243, v135
	s_mov_b64 exec, -1
.Lsel_h2s93:
	v_xor_b32_e32 v244, s57, v94
	v_cmp_gt_u32_e32 vcc, s86, v244
	s_cbranch_vccz .Lsel_h2s94
	s_mov_b64 exec, vcc
	v_lshl_add_u32 v245, v244, 2, v136
	ds_add_u32 v245, v135
	s_mov_b64 exec, -1
.Lsel_h2s94:
	v_xor_b32_e32 v246, s57, v95
	v_cmp_gt_u32_e32 vcc, s86, v246
	s_cbranch_vccz .Lsel_h2s95
	s_mov_b64 exec, vcc
	v_lshl_add_u32 v247, v246, 2, v136
	ds_add_u32 v247, v135
	s_mov_b64 exec, -1
.Lsel_h2s95:
	s_cmpk_le_u32 s34, 96
	s_cbranch_scc1 .Lsel_hist_done
	v_xor_b32_e32 v240, s57, v208
	v_cmp_gt_u32_e32 vcc, s86, v240
	s_cbranch_vccz .Lsel_h2s96
	s_mov_b64 exec, vcc
	v_lshl_add_u32 v241, v240, 2, v136
	ds_add_u32 v241, v135
	s_mov_b64 exec, -1
.Lsel_h2s96:
	v_xor_b32_e32 v242, s57, v209
	v_cmp_gt_u32_e32 vcc, s86, v242
	s_cbranch_vccz .Lsel_h2s97
	s_mov_b64 exec, vcc
	v_lshl_add_u32 v243, v242, 2, v136
	ds_add_u32 v243, v135
	s_mov_b64 exec, -1
.Lsel_h2s97:
	v_xor_b32_e32 v244, s57, v210
	v_cmp_gt_u32_e32 vcc, s86, v244
	s_cbranch_vccz .Lsel_h2s98
	s_mov_b64 exec, vcc
	v_lshl_add_u32 v245, v244, 2, v136
	ds_add_u32 v245, v135
	s_mov_b64 exec, -1
.Lsel_h2s98:
	v_xor_b32_e32 v246, s57, v211
	v_cmp_gt_u32_e32 vcc, s86, v246
	s_cbranch_vccz .Lsel_h2s99
	s_mov_b64 exec, vcc
	v_lshl_add_u32 v247, v246, 2, v136
	ds_add_u32 v247, v135
	s_mov_b64 exec, -1
.Lsel_h2s99:
	v_xor_b32_e32 v240, s57, v212
	v_cmp_gt_u32_e32 vcc, s86, v240
	s_cbranch_vccz .Lsel_h2s100
	s_mov_b64 exec, vcc
	v_lshl_add_u32 v241, v240, 2, v136
	ds_add_u32 v241, v135
	s_mov_b64 exec, -1
.Lsel_h2s100:
	v_xor_b32_e32 v242, s57, v213
	v_cmp_gt_u32_e32 vcc, s86, v242
	s_cbranch_vccz .Lsel_h2s101
	s_mov_b64 exec, vcc
	v_lshl_add_u32 v243, v242, 2, v136
	ds_add_u32 v243, v135
	s_mov_b64 exec, -1
.Lsel_h2s101:
	v_xor_b32_e32 v244, s57, v214
	v_cmp_gt_u32_e32 vcc, s86, v244
	s_cbranch_vccz .Lsel_h2s102
	s_mov_b64 exec, vcc
	v_lshl_add_u32 v245, v244, 2, v136
	ds_add_u32 v245, v135
	s_mov_b64 exec, -1
.Lsel_h2s102:
	v_xor_b32_e32 v246, s57, v215
	v_cmp_gt_u32_e32 vcc, s86, v246
	s_cbranch_vccz .Lsel_h2s103
	s_mov_b64 exec, vcc
	v_lshl_add_u32 v247, v246, 2, v136
	ds_add_u32 v247, v135
	s_mov_b64 exec, -1
.Lsel_h2s103:
	v_xor_b32_e32 v240, s57, v216
	v_cmp_gt_u32_e32 vcc, s86, v240
	s_cbranch_vccz .Lsel_h2s104
	s_mov_b64 exec, vcc
	v_lshl_add_u32 v241, v240, 2, v136
	ds_add_u32 v241, v135
	s_mov_b64 exec, -1
.Lsel_h2s104:
	v_xor_b32_e32 v242, s57, v217
	v_cmp_gt_u32_e32 vcc, s86, v242
	s_cbranch_vccz .Lsel_h2s105
	s_mov_b64 exec, vcc
	v_lshl_add_u32 v243, v242, 2, v136
	ds_add_u32 v243, v135
	s_mov_b64 exec, -1
.Lsel_h2s105:
	v_xor_b32_e32 v244, s57, v218
	v_cmp_gt_u32_e32 vcc, s86, v244
	s_cbranch_vccz .Lsel_h2s106
	s_mov_b64 exec, vcc
	v_lshl_add_u32 v245, v244, 2, v136
	ds_add_u32 v245, v135
	s_mov_b64 exec, -1
.Lsel_h2s106:
	v_xor_b32_e32 v246, s57, v219
	v_cmp_gt_u32_e32 vcc, s86, v246
	s_cbranch_vccz .Lsel_h2s107
	s_mov_b64 exec, vcc
	v_lshl_add_u32 v247, v246, 2, v136
	ds_add_u32 v247, v135
	s_mov_b64 exec, -1
.Lsel_h2s107:
	v_xor_b32_e32 v240, s57, v220
	v_cmp_gt_u32_e32 vcc, s86, v240
	s_cbranch_vccz .Lsel_h2s108
	s_mov_b64 exec, vcc
	v_lshl_add_u32 v241, v240, 2, v136
	ds_add_u32 v241, v135
	s_mov_b64 exec, -1
.Lsel_h2s108:
	v_xor_b32_e32 v242, s57, v221
	v_cmp_gt_u32_e32 vcc, s86, v242
	s_cbranch_vccz .Lsel_h2s109
	s_mov_b64 exec, vcc
	v_lshl_add_u32 v243, v242, 2, v136
	ds_add_u32 v243, v135
	s_mov_b64 exec, -1
.Lsel_h2s109:
	v_xor_b32_e32 v244, s57, v222
	v_cmp_gt_u32_e32 vcc, s86, v244
	s_cbranch_vccz .Lsel_h2s110
	s_mov_b64 exec, vcc
	v_lshl_add_u32 v245, v244, 2, v136
	ds_add_u32 v245, v135
	s_mov_b64 exec, -1
.Lsel_h2s110:
	v_xor_b32_e32 v246, s57, v223
	v_cmp_gt_u32_e32 vcc, s86, v246
	s_cbranch_vccz .Lsel_h2s111
	s_mov_b64 exec, vcc
	v_lshl_add_u32 v247, v246, 2, v136
	ds_add_u32 v247, v135
	s_mov_b64 exec, -1
.Lsel_h2s111:
	s_cmpk_le_u32 s34, 112
	s_cbranch_scc1 .Lsel_hist_done
	v_xor_b32_e32 v240, s57, v224
	v_cmp_gt_u32_e32 vcc, s86, v240
	s_cbranch_vccz .Lsel_h2s112
	s_mov_b64 exec, vcc
	v_lshl_add_u32 v241, v240, 2, v136
	ds_add_u32 v241, v135
	s_mov_b64 exec, -1
.Lsel_h2s112:
	v_xor_b32_e32 v242, s57, v225
	v_cmp_gt_u32_e32 vcc, s86, v242
	s_cbranch_vccz .Lsel_h2s113
	s_mov_b64 exec, vcc
	v_lshl_add_u32 v243, v242, 2, v136
	ds_add_u32 v243, v135
	s_mov_b64 exec, -1
.Lsel_h2s113:
	v_xor_b32_e32 v244, s57, v226
	v_cmp_gt_u32_e32 vcc, s86, v244
	s_cbranch_vccz .Lsel_h2s114
	s_mov_b64 exec, vcc
	v_lshl_add_u32 v245, v244, 2, v136
	ds_add_u32 v245, v135
	s_mov_b64 exec, -1
.Lsel_h2s114:
	v_xor_b32_e32 v246, s57, v227
	v_cmp_gt_u32_e32 vcc, s86, v246
	s_cbranch_vccz .Lsel_h2s115
	s_mov_b64 exec, vcc
	v_lshl_add_u32 v247, v246, 2, v136
	ds_add_u32 v247, v135
	s_mov_b64 exec, -1
.Lsel_h2s115:
	v_xor_b32_e32 v240, s57, v228
	v_cmp_gt_u32_e32 vcc, s86, v240
	s_cbranch_vccz .Lsel_h2s116
	s_mov_b64 exec, vcc
	v_lshl_add_u32 v241, v240, 2, v136
	ds_add_u32 v241, v135
	s_mov_b64 exec, -1
.Lsel_h2s116:
	v_xor_b32_e32 v242, s57, v229
	v_cmp_gt_u32_e32 vcc, s86, v242
	s_cbranch_vccz .Lsel_h2s117
	s_mov_b64 exec, vcc
	v_lshl_add_u32 v243, v242, 2, v136
	ds_add_u32 v243, v135
	s_mov_b64 exec, -1
.Lsel_h2s117:
	v_xor_b32_e32 v244, s57, v230
	v_cmp_gt_u32_e32 vcc, s86, v244
	s_cbranch_vccz .Lsel_h2s118
	s_mov_b64 exec, vcc
	v_lshl_add_u32 v245, v244, 2, v136
	ds_add_u32 v245, v135
	s_mov_b64 exec, -1
.Lsel_h2s118:
	v_xor_b32_e32 v246, s57, v231
	v_cmp_gt_u32_e32 vcc, s86, v246
	s_cbranch_vccz .Lsel_h2s119
	s_mov_b64 exec, vcc
	v_lshl_add_u32 v247, v246, 2, v136
	ds_add_u32 v247, v135
	s_mov_b64 exec, -1
.Lsel_h2s119:
	v_xor_b32_e32 v240, s57, v232
	v_cmp_gt_u32_e32 vcc, s86, v240
	s_cbranch_vccz .Lsel_h2s120
	s_mov_b64 exec, vcc
	v_lshl_add_u32 v241, v240, 2, v136
	ds_add_u32 v241, v135
	s_mov_b64 exec, -1
.Lsel_h2s120:
	v_xor_b32_e32 v242, s57, v233
	v_cmp_gt_u32_e32 vcc, s86, v242
	s_cbranch_vccz .Lsel_h2s121
	s_mov_b64 exec, vcc
	v_lshl_add_u32 v243, v242, 2, v136
	ds_add_u32 v243, v135
	s_mov_b64 exec, -1
.Lsel_h2s121:
	v_xor_b32_e32 v244, s57, v234
	v_cmp_gt_u32_e32 vcc, s86, v244
	s_cbranch_vccz .Lsel_h2s122
	s_mov_b64 exec, vcc
	v_lshl_add_u32 v245, v244, 2, v136
	ds_add_u32 v245, v135
	s_mov_b64 exec, -1
.Lsel_h2s122:
	v_xor_b32_e32 v246, s57, v235
	v_cmp_gt_u32_e32 vcc, s86, v246
	s_cbranch_vccz .Lsel_h2s123
	s_mov_b64 exec, vcc
	v_lshl_add_u32 v247, v246, 2, v136
	ds_add_u32 v247, v135
	s_mov_b64 exec, -1
.Lsel_h2s123:
	v_xor_b32_e32 v240, s57, v236
	v_cmp_gt_u32_e32 vcc, s86, v240
	s_cbranch_vccz .Lsel_h2s124
	s_mov_b64 exec, vcc
	v_lshl_add_u32 v241, v240, 2, v136
	ds_add_u32 v241, v135
	s_mov_b64 exec, -1
.Lsel_h2s124:
	v_xor_b32_e32 v242, s57, v237
	v_cmp_gt_u32_e32 vcc, s86, v242
	s_cbranch_vccz .Lsel_h2s125
	s_mov_b64 exec, vcc
	v_lshl_add_u32 v243, v242, 2, v136
	ds_add_u32 v243, v135
	s_mov_b64 exec, -1
.Lsel_h2s125:
	v_xor_b32_e32 v244, s57, v238
	v_cmp_gt_u32_e32 vcc, s86, v244
	s_cbranch_vccz .Lsel_h2s126
	s_mov_b64 exec, vcc
	v_lshl_add_u32 v245, v244, 2, v136
	ds_add_u32 v245, v135
	s_mov_b64 exec, -1
.Lsel_h2s126:
	v_xor_b32_e32 v246, s57, v239
	v_cmp_gt_u32_e32 vcc, s86, v246
	s_cbranch_vccz .Lsel_h2s127
	s_mov_b64 exec, vcc
	v_lshl_add_u32 v247, v246, 2, v136
	ds_add_u32 v247, v135
	s_mov_b64 exec, -1
.Lsel_h2s127:
	s_branch .Lsel_hist_done

.Lsel_final:
	s_cmp_lg_u32 s56, s91
	s_cbranch_scc1 .Lsel_final_slow
	v_cmp_le_u32_e64 s[96:97], v0, s57
	v_cmp_le_u32_e64 s[54:55], v1, s57
	v_cmp_le_u32_e64 s[98:99], v2, s57
	v_cmp_le_u32_e64 s[52:53], v3, s57
	s_nop 0
	v_writelane_b32 v250, s96, 0
	v_writelane_b32 v251, s97, 0
	v_writelane_b32 v250, s54, 1
	v_writelane_b32 v251, s55, 1
	v_writelane_b32 v250, s98, 2
	v_writelane_b32 v251, s99, 2
	v_writelane_b32 v250, s52, 3
	v_writelane_b32 v251, s53, 3
	v_cmp_le_u32_e64 s[96:97], v4, s57
	v_cmp_le_u32_e64 s[54:55], v5, s57
	v_cmp_le_u32_e64 s[98:99], v6, s57
	v_cmp_le_u32_e64 s[52:53], v7, s57
	s_nop 0
	v_writelane_b32 v250, s96, 4
	v_writelane_b32 v251, s97, 4
	v_writelane_b32 v250, s54, 5
	v_writelane_b32 v251, s55, 5
	v_writelane_b32 v250, s98, 6
	v_writelane_b32 v251, s99, 6
	v_writelane_b32 v250, s52, 7
	v_writelane_b32 v251, s53, 7
	v_cmp_le_u32_e64 s[96:97], v8, s57
	v_cmp_le_u32_e64 s[54:55], v9, s57
	v_cmp_le_u32_e64 s[98:99], v10, s57
	v_cmp_le_u32_e64 s[52:53], v11, s57
	s_nop 0
	v_writelane_b32 v250, s96, 8
	v_writelane_b32 v251, s97, 8
	v_writelane_b32 v250, s54, 9
	v_writelane_b32 v251, s55, 9
	v_writelane_b32 v250, s98, 10
	v_writelane_b32 v251, s99, 10
	v_writelane_b32 v250, s52, 11
	v_writelane_b32 v251, s53, 11
	v_cmp_le_u32_e64 s[96:97], v12, s57
	v_cmp_le_u32_e64 s[54:55], v13, s57
	v_cmp_le_u32_e64 s[98:99], v14, s57
	v_cmp_le_u32_e64 s[52:53], v15, s57
	s_nop 0
	v_writelane_b32 v250, s96, 12
	v_writelane_b32 v251, s97, 12
	v_writelane_b32 v250, s54, 13
	v_writelane_b32 v251, s55, 13
	v_writelane_b32 v250, s98, 14
	v_writelane_b32 v251, s99, 14
	v_writelane_b32 v250, s52, 15
	v_writelane_b32 v251, s53, 15
	s_cmpk_le_u32 s34, 16
	s_cbranch_scc1 .Lsel_store
	v_cmp_le_u32_e64 s[96:97], v16, s57
	v_cmp_le_u32_e64 s[54:55], v17, s57
	v_cmp_le_u32_e64 s[98:99], v18, s57
	v_cmp_le_u32_e64 s[52:53], v19, s57
	s_nop 0
	v_writelane_b32 v250, s96, 16
	v_writelane_b32 v251, s97, 16
	v_writelane_b32 v250, s54, 17
	v_writelane_b32 v251, s55, 17
	v_writelane_b32 v250, s98, 18
	v_writelane_b32 v251, s99, 18
	v_writelane_b32 v250, s52, 19
	v_writelane_b32 v251, s53, 19
	v_cmp_le_u32_e64 s[96:97], v20, s57
	v_cmp_le_u32_e64 s[54:55], v21, s57
	v_cmp_le_u32_e64 s[98:99], v22, s57
	v_cmp_le_u32_e64 s[52:53], v23, s57
	s_nop 0
	v_writelane_b32 v250, s96, 20
	v_writelane_b32 v251, s97, 20
	v_writelane_b32 v250, s54, 21
	v_writelane_b32 v251, s55, 21
	v_writelane_b32 v250, s98, 22
	v_writelane_b32 v251, s99, 22
	v_writelane_b32 v250, s52, 23
	v_writelane_b32 v251, s53, 23
	v_cmp_le_u32_e64 s[96:97], v24, s57
	v_cmp_le_u32_e64 s[54:55], v25, s57
	v_cmp_le_u32_e64 s[98:99], v26, s57
	v_cmp_le_u32_e64 s[52:53], v27, s57
	s_nop 0
	v_writelane_b32 v250, s96, 24
	v_writelane_b32 v251, s97, 24
	v_writelane_b32 v250, s54, 25
	v_writelane_b32 v251, s55, 25
	v_writelane_b32 v250, s98, 26
	v_writelane_b32 v251, s99, 26
	v_writelane_b32 v250, s52, 27
	v_writelane_b32 v251, s53, 27
	v_cmp_le_u32_e64 s[96:97], v28, s57
	v_cmp_le_u32_e64 s[54:55], v29, s57
	v_cmp_le_u32_e64 s[98:99], v30, s57
	v_cmp_le_u32_e64 s[52:53], v31, s57
	s_nop 0
	v_writelane_b32 v250, s96, 28
	v_writelane_b32 v251, s97, 28
	v_writelane_b32 v250, s54, 29
	v_writelane_b32 v251, s55, 29
	v_writelane_b32 v250, s98, 30
	v_writelane_b32 v251, s99, 30
	v_writelane_b32 v250, s52, 31
	v_writelane_b32 v251, s53, 31
	s_cmpk_le_u32 s34, 32
	s_cbranch_scc1 .Lsel_store
	v_cmp_le_u32_e64 s[96:97], v32, s57
	v_cmp_le_u32_e64 s[54:55], v33, s57
	v_cmp_le_u32_e64 s[98:99], v34, s57
	v_cmp_le_u32_e64 s[52:53], v35, s57
	s_nop 0
	v_writelane_b32 v250, s96, 32
	v_writelane_b32 v251, s97, 32
	v_writelane_b32 v250, s54, 33
	v_writelane_b32 v251, s55, 33
	v_writelane_b32 v250, s98, 34
	v_writelane_b32 v251, s99, 34
	v_writelane_b32 v250, s52, 35
	v_writelane_b32 v251, s53, 35
	v_cmp_le_u32_e64 s[96:97], v36, s57
	v_cmp_le_u32_e64 s[54:55], v37, s57
	v_cmp_le_u32_e64 s[98:99], v38, s57
	v_cmp_le_u32_e64 s[52:53], v39, s57
	s_nop 0
	v_writelane_b32 v250, s96, 36
	v_writelane_b32 v251, s97, 36
	v_writelane_b32 v250, s54, 37
	v_writelane_b32 v251, s55, 37
	v_writelane_b32 v250, s98, 38
	v_writelane_b32 v251, s99, 38
	v_writelane_b32 v250, s52, 39
	v_writelane_b32 v251, s53, 39
	v_cmp_le_u32_e64 s[96:97], v40, s57
	v_cmp_le_u32_e64 s[54:55], v41, s57
	v_cmp_le_u32_e64 s[98:99], v42, s57
	v_cmp_le_u32_e64 s[52:53], v43, s57
	s_nop 0
	v_writelane_b32 v250, s96, 40
	v_writelane_b32 v251, s97, 40
	v_writelane_b32 v250, s54, 41
	v_writelane_b32 v251, s55, 41
	v_writelane_b32 v250, s98, 42
	v_writelane_b32 v251, s99, 42
	v_writelane_b32 v250, s52, 43
	v_writelane_b32 v251, s53, 43
	v_cmp_le_u32_e64 s[96:97], v44, s57
	v_cmp_le_u32_e64 s[54:55], v45, s57
	v_cmp_le_u32_e64 s[98:99], v46, s57
	v_cmp_le_u32_e64 s[52:53], v47, s57
	s_nop 0
	v_writelane_b32 v250, s96, 44
	v_writelane_b32 v251, s97, 44
	v_writelane_b32 v250, s54, 45
	v_writelane_b32 v251, s55, 45
	v_writelane_b32 v250, s98, 46
	v_writelane_b32 v251, s99, 46
	v_writelane_b32 v250, s52, 47
	v_writelane_b32 v251, s53, 47
	s_cmpk_le_u32 s34, 48
	s_cbranch_scc1 .Lsel_store
	v_cmp_le_u32_e64 s[96:97], v48, s57
	v_cmp_le_u32_e64 s[54:55], v49, s57
	v_cmp_le_u32_e64 s[98:99], v50, s57
	v_cmp_le_u32_e64 s[52:53], v51, s57
	s_nop 0
	v_writelane_b32 v250, s96, 48
	v_writelane_b32 v251, s97, 48
	v_writelane_b32 v250, s54, 49
	v_writelane_b32 v251, s55, 49
	v_writelane_b32 v250, s98, 50
	v_writelane_b32 v251, s99, 50
	v_writelane_b32 v250, s52, 51
	v_writelane_b32 v251, s53, 51
	v_cmp_le_u32_e64 s[96:97], v52, s57
	v_cmp_le_u32_e64 s[54:55], v53, s57
	v_cmp_le_u32_e64 s[98:99], v54, s57
	v_cmp_le_u32_e64 s[52:53], v55, s57
	s_nop 0
	v_writelane_b32 v250, s96, 52
	v_writelane_b32 v251, s97, 52
	v_writelane_b32 v250, s54, 53
	v_writelane_b32 v251, s55, 53
	v_writelane_b32 v250, s98, 54
	v_writelane_b32 v251, s99, 54
	v_writelane_b32 v250, s52, 55
	v_writelane_b32 v251, s53, 55
	v_cmp_le_u32_e64 s[96:97], v56, s57
	v_cmp_le_u32_e64 s[54:55], v57, s57
	v_cmp_le_u32_e64 s[98:99], v58, s57
	v_cmp_le_u32_e64 s[52:53], v59, s57
	s_nop 0
	v_writelane_b32 v250, s96, 56
	v_writelane_b32 v251, s97, 56
	v_writelane_b32 v250, s54, 57
	v_writelane_b32 v251, s55, 57
	v_writelane_b32 v250, s98, 58
	v_writelane_b32 v251, s99, 58
	v_writelane_b32 v250, s52, 59
	v_writelane_b32 v251, s53, 59
	v_cmp_le_u32_e64 s[96:97], v60, s57
	v_cmp_le_u32_e64 s[54:55], v61, s57
	v_cmp_le_u32_e64 s[98:99], v62, s57
	v_cmp_le_u32_e64 s[52:53], v63, s57
	s_nop 0
	v_writelane_b32 v250, s96, 60
	v_writelane_b32 v251, s97, 60
	v_writelane_b32 v250, s54, 61
	v_writelane_b32 v251, s55, 61
	v_writelane_b32 v250, s98, 62
	v_writelane_b32 v251, s99, 62
	v_writelane_b32 v250, s52, 63
	v_writelane_b32 v251, s53, 63
	s_cmpk_le_u32 s34, 64
	s_cbranch_scc1 .Lsel_store
	v_cmp_le_u32_e64 s[96:97], v64, s57
	v_cmp_le_u32_e64 s[54:55], v65, s57
	v_cmp_le_u32_e64 s[98:99], v66, s57
	v_cmp_le_u32_e64 s[52:53], v67, s57
	s_nop 0
	v_writelane_b32 v252, s96, 0
	v_writelane_b32 v253, s97, 0
	v_writelane_b32 v252, s54, 1
	v_writelane_b32 v253, s55, 1
	v_writelane_b32 v252, s98, 2
	v_writelane_b32 v253, s99, 2
	v_writelane_b32 v252, s52, 3
	v_writelane_b32 v253, s53, 3
	v_cmp_le_u32_e64 s[96:97], v68, s57
	v_cmp_le_u32_e64 s[54:55], v69, s57
	v_cmp_le_u32_e64 s[98:99], v70, s57
	v_cmp_le_u32_e64 s[52:53], v71, s57
	s_nop 0
	v_writelane_b32 v252, s96, 4
	v_writelane_b32 v253, s97, 4
	v_writelane_b32 v252, s54, 5
	v_writelane_b32 v253, s55, 5
	v_writelane_b32 v252, s98, 6
	v_writelane_b32 v253, s99, 6
	v_writelane_b32 v252, s52, 7
	v_writelane_b32 v253, s53, 7
	v_cmp_le_u32_e64 s[96:97], v72, s57
	v_cmp_le_u32_e64 s[54:55], v73, s57
	v_cmp_le_u32_e64 s[98:99], v74, s57
	v_cmp_le_u32_e64 s[52:53], v75, s57
	s_nop 0
	v_writelane_b32 v252, s96, 8
	v_writelane_b32 v253, s97, 8
	v_writelane_b32 v252, s54, 9
	v_writelane_b32 v253, s55, 9
	v_writelane_b32 v252, s98, 10
	v_writelane_b32 v253, s99, 10
	v_writelane_b32 v252, s52, 11
	v_writelane_b32 v253, s53, 11
	v_cmp_le_u32_e64 s[96:97], v76, s57
	v_cmp_le_u32_e64 s[54:55], v77, s57
	v_cmp_le_u32_e64 s[98:99], v78, s57
	v_cmp_le_u32_e64 s[52:53], v79, s57
	s_nop 0
	v_writelane_b32 v252, s96, 12
	v_writelane_b32 v253, s97, 12
	v_writelane_b32 v252, s54, 13
	v_writelane_b32 v253, s55, 13
	v_writelane_b32 v252, s98, 14
	v_writelane_b32 v253, s99, 14
	v_writelane_b32 v252, s52, 15
	v_writelane_b32 v253, s53, 15
	s_cmpk_le_u32 s34, 80
	s_cbranch_scc1 .Lsel_store
	v_cmp_le_u32_e64 s[96:97], v80, s57
	v_cmp_le_u32_e64 s[54:55], v81, s57
	v_cmp_le_u32_e64 s[98:99], v82, s57
	v_cmp_le_u32_e64 s[52:53], v83, s57
	s_nop 0
	v_writelane_b32 v252, s96, 16
	v_writelane_b32 v253, s97, 16
	v_writelane_b32 v252, s54, 17
	v_writelane_b32 v253, s55, 17
	v_writelane_b32 v252, s98, 18
	v_writelane_b32 v253, s99, 18
	v_writelane_b32 v252, s52, 19
	v_writelane_b32 v253, s53, 19
	v_cmp_le_u32_e64 s[96:97], v84, s57
	v_cmp_le_u32_e64 s[54:55], v85, s57
	v_cmp_le_u32_e64 s[98:99], v86, s57
	v_cmp_le_u32_e64 s[52:53], v87, s57
	s_nop 0
	v_writelane_b32 v252, s96, 20
	v_writelane_b32 v253, s97, 20
	v_writelane_b32 v252, s54, 21
	v_writelane_b32 v253, s55, 21
	v_writelane_b32 v252, s98, 22
	v_writelane_b32 v253, s99, 22
	v_writelane_b32 v252, s52, 23
	v_writelane_b32 v253, s53, 23
	v_cmp_le_u32_e64 s[96:97], v88, s57
	v_cmp_le_u32_e64 s[54:55], v89, s57
	v_cmp_le_u32_e64 s[98:99], v90, s57
	v_cmp_le_u32_e64 s[52:53], v91, s57
	s_nop 0
	v_writelane_b32 v252, s96, 24
	v_writelane_b32 v253, s97, 24
	v_writelane_b32 v252, s54, 25
	v_writelane_b32 v253, s55, 25
	v_writelane_b32 v252, s98, 26
	v_writelane_b32 v253, s99, 26
	v_writelane_b32 v252, s52, 27
	v_writelane_b32 v253, s53, 27
	v_cmp_le_u32_e64 s[96:97], v92, s57
	v_cmp_le_u32_e64 s[54:55], v93, s57
	v_cmp_le_u32_e64 s[98:99], v94, s57
	v_cmp_le_u32_e64 s[52:53], v95, s57
	s_nop 0
	v_writelane_b32 v252, s96, 28
	v_writelane_b32 v253, s97, 28
	v_writelane_b32 v252, s54, 29
	v_writelane_b32 v253, s55, 29
	v_writelane_b32 v252, s98, 30
	v_writelane_b32 v253, s99, 30
	v_writelane_b32 v252, s52, 31
	v_writelane_b32 v253, s53, 31
	s_cmpk_le_u32 s34, 96
	s_cbranch_scc1 .Lsel_store
	v_cmp_le_u32_e64 s[96:97], v208, s57
	v_cmp_le_u32_e64 s[54:55], v209, s57
	v_cmp_le_u32_e64 s[98:99], v210, s57
	v_cmp_le_u32_e64 s[52:53], v211, s57
	s_nop 0
	v_writelane_b32 v252, s96, 32
	v_writelane_b32 v253, s97, 32
	v_writelane_b32 v252, s54, 33
	v_writelane_b32 v253, s55, 33
	v_writelane_b32 v252, s98, 34
	v_writelane_b32 v253, s99, 34
	v_writelane_b32 v252, s52, 35
	v_writelane_b32 v253, s53, 35
	v_cmp_le_u32_e64 s[96:97], v212, s57
	v_cmp_le_u32_e64 s[54:55], v213, s57
	v_cmp_le_u32_e64 s[98:99], v214, s57
	v_cmp_le_u32_e64 s[52:53], v215, s57
	s_nop 0
	v_writelane_b32 v252, s96, 36
	v_writelane_b32 v253, s97, 36
	v_writelane_b32 v252, s54, 37
	v_writelane_b32 v253, s55, 37
	v_writelane_b32 v252, s98, 38
	v_writelane_b32 v253, s99, 38
	v_writelane_b32 v252, s52, 39
	v_writelane_b32 v253, s53, 39
	v_cmp_le_u32_e64 s[96:97], v216, s57
	v_cmp_le_u32_e64 s[54:55], v217, s57
	v_cmp_le_u32_e64 s[98:99], v218, s57
	v_cmp_le_u32_e64 s[52:53], v219, s57
	s_nop 0
	v_writelane_b32 v252, s96, 40
	v_writelane_b32 v253, s97, 40
	v_writelane_b32 v252, s54, 41
	v_writelane_b32 v253, s55, 41
	v_writelane_b32 v252, s98, 42
	v_writelane_b32 v253, s99, 42
	v_writelane_b32 v252, s52, 43
	v_writelane_b32 v253, s53, 43
	v_cmp_le_u32_e64 s[96:97], v220, s57
	v_cmp_le_u32_e64 s[54:55], v221, s57
	v_cmp_le_u32_e64 s[98:99], v222, s57
	v_cmp_le_u32_e64 s[52:53], v223, s57
	s_nop 0
	v_writelane_b32 v252, s96, 44
	v_writelane_b32 v253, s97, 44
	v_writelane_b32 v252, s54, 45
	v_writelane_b32 v253, s55, 45
	v_writelane_b32 v252, s98, 46
	v_writelane_b32 v253, s99, 46
	v_writelane_b32 v252, s52, 47
	v_writelane_b32 v253, s53, 47
	s_cmpk_le_u32 s34, 112
	s_cbranch_scc1 .Lsel_store
	v_cmp_le_u32_e64 s[96:97], v224, s57
	v_cmp_le_u32_e64 s[54:55], v225, s57
	v_cmp_le_u32_e64 s[98:99], v226, s57
	v_cmp_le_u32_e64 s[52:53], v227, s57
	s_nop 0
	v_writelane_b32 v252, s96, 48
	v_writelane_b32 v253, s97, 48
	v_writelane_b32 v252, s54, 49
	v_writelane_b32 v253, s55, 49
	v_writelane_b32 v252, s98, 50
	v_writelane_b32 v253, s99, 50
	v_writelane_b32 v252, s52, 51
	v_writelane_b32 v253, s53, 51
	v_cmp_le_u32_e64 s[96:97], v228, s57
	v_cmp_le_u32_e64 s[54:55], v229, s57
	v_cmp_le_u32_e64 s[98:99], v230, s57
	v_cmp_le_u32_e64 s[52:53], v231, s57
	s_nop 0
	v_writelane_b32 v252, s96, 52
	v_writelane_b32 v253, s97, 52
	v_writelane_b32 v252, s54, 53
	v_writelane_b32 v253, s55, 53
	v_writelane_b32 v252, s98, 54
	v_writelane_b32 v253, s99, 54
	v_writelane_b32 v252, s52, 55
	v_writelane_b32 v253, s53, 55
	v_cmp_le_u32_e64 s[96:97], v232, s57
	v_cmp_le_u32_e64 s[54:55], v233, s57
	v_cmp_le_u32_e64 s[98:99], v234, s57
	v_cmp_le_u32_e64 s[52:53], v235, s57
	s_nop 0
	v_writelane_b32 v252, s96, 56
	v_writelane_b32 v253, s97, 56
	v_writelane_b32 v252, s54, 57
	v_writelane_b32 v253, s55, 57
	v_writelane_b32 v252, s98, 58
	v_writelane_b32 v253, s99, 58
	v_writelane_b32 v252, s52, 59
	v_writelane_b32 v253, s53, 59
	v_cmp_le_u32_e64 s[96:97], v236, s57
	v_cmp_le_u32_e64 s[54:55], v237, s57
	v_cmp_le_u32_e64 s[98:99], v238, s57
	v_cmp_le_u32_e64 s[52:53], v239, s57
	s_nop 0
	v_writelane_b32 v252, s96, 60
	v_writelane_b32 v253, s97, 60
	v_writelane_b32 v252, s54, 61
	v_writelane_b32 v253, s55, 61
	v_writelane_b32 v252, s98, 62
	v_writelane_b32 v253, s99, 62
	v_writelane_b32 v252, s52, 63
	v_writelane_b32 v253, s53, 63
	s_branch .Lsel_store
